# LRU-B conv section: the four lone ds_read_u16 (load-wait-use ladders) issued one VALU block earlier into v249
# speedup vs baseline: 1.0066x; 1.0066x over previous
; #define LAS __attribute__((address_space(3)))
; __device__ __forceinline__ unsigned pk2(float lo, float hi) { return f2bf(lo) | (f2bf(hi) << 16); }
; template <bool PHASE_B>
; __device__ __forceinline__ void lru_item(const Params& p, LAS unsigned char* lds, int ci, int ci_next, int jb, const int tid, v4u (&xvn)[3]) {
;     ...
;     for (int ks = 0; ks < 2; ++ks) { const int cb0 = 32 * ks + 8 * fq;
;         f32x4 s0 = *(const LAS f32x4*)(CB + cb0), s1 = *(const LAS f32x4*)(CB + cb0 + 4);
; #pragma unroll
;         for (int tap = 0; tap < 4; ++tap) { const v4u v = *(const LAS v4u*)(lds + LR_XR + (16 * rt + fr + tap) * 144 + cb0 * 2);
;             const f32x4 w0 = *(const LAS f32x4*)(CW + tap * 64 + cb0), w1 = *(const LAS f32x4*)(CW + tap * 64 + cb0 + 4);
;             s0 += (f32x4){bflo(v.x), bfhi(v.x), bflo(v.y), bfhi(v.y)} * w0; s1 += (f32x4){bflo(v.z), bfhi(v.z), bflo(v.w), bfhi(v.w)} * w1; }
;         v4u o; o.x = pk2(s0[0], s0[1]); o.y = pk2(s0[2], s0[3]); o.z = pk2(s1[0], s1[1]); o.w = pk2(s1[2], s1[3]);
;         af[ks] = __builtin_bit_cast(bf16x8, o); }
.LBB0_339:
	v_add_u32_e32 v1, v167, v157
	ds_read_b128 v[14:17], v165 offset:56832
	ds_read_b128 v[18:21], v165 offset:56848
	ds_read_b128 v[22:25], v1
	v_add_u32_e32 v31, v167, v166
	ds_read_b128 v[26:29], v31 offset:55808
	ds_read_b128 v[36:39], v31 offset:55824
	v_add_u32_e32 v50, 0xd800, v170
	v_add_u32_e32 v51, 0xdc00, v170
	s_waitcnt lgkmcnt(2)
	v_lshlrev_b32_e32 v40, 16, v22
	v_and_b32_e32 v41, 0xffff0000, v22
	v_lshlrev_b32_e32 v22, 16, v23
	v_and_b32_e32 v23, 0xffff0000, v23
	s_waitcnt lgkmcnt(1)
	v_pk_fma_f32 v[28:29], v[28:29], v[22:23], v[16:17]
	v_pk_fma_f32 v[26:27], v[26:27], v[40:41], v[14:15]
	v_lshlrev_b32_e32 v14, 16, v24
	v_and_b32_e32 v15, 0xffff0000, v24
	v_lshlrev_b32_e32 v16, 16, v25
	v_and_b32_e32 v17, 0xffff0000, v25
	s_waitcnt lgkmcnt(0)
	v_pk_fma_f32 v[38:39], v[38:39], v[16:17], v[20:21]
	v_pk_fma_f32 v[36:37], v[36:37], v[14:15], v[18:19]
	ds_read_b128 v[14:17], v1 offset:144
	ds_read_b128 v[18:21], v31 offset:56064
	ds_read_b128 v[22:25], v31 offset:56080
	v_add_u32_e32 v132, v173, v166
	s_and_b64 vcc, exec, s[6:7]
	s_waitcnt lgkmcnt(2)
	v_lshlrev_b32_e32 v40, 16, v14
	v_and_b32_e32 v41, 0xffff0000, v14
	v_lshlrev_b32_e32 v14, 16, v15
	v_and_b32_e32 v15, 0xffff0000, v15
	s_waitcnt lgkmcnt(1)
	v_pk_fma_f32 v[28:29], v[20:21], v[14:15], v[28:29]
	v_lshlrev_b32_e32 v14, 16, v16
	v_and_b32_e32 v15, 0xffff0000, v16
	v_lshlrev_b32_e32 v16, 16, v17
	v_and_b32_e32 v17, 0xffff0000, v17
	v_pk_fma_f32 v[26:27], v[18:19], v[40:41], v[26:27]
	s_waitcnt lgkmcnt(0)
	v_pk_fma_f32 v[38:39], v[24:25], v[16:17], v[38:39]
	v_pk_fma_f32 v[36:37], v[22:23], v[14:15], v[36:37]
	ds_read_b128 v[14:17], v1 offset:288
	ds_read_b128 v[18:21], v31 offset:56320
	ds_read_b128 v[22:25], v31 offset:56336
	s_waitcnt lgkmcnt(2)
	v_lshlrev_b32_e32 v40, 16, v14
	v_and_b32_e32 v41, 0xffff0000, v14
	v_lshlrev_b32_e32 v14, 16, v15
	v_and_b32_e32 v15, 0xffff0000, v15
	s_waitcnt lgkmcnt(1)
	v_pk_fma_f32 v[28:29], v[20:21], v[14:15], v[28:29]
	v_lshlrev_b32_e32 v14, 16, v16
	v_and_b32_e32 v15, 0xffff0000, v16
	v_lshlrev_b32_e32 v16, 16, v17
	v_and_b32_e32 v17, 0xffff0000, v17
	v_pk_fma_f32 v[26:27], v[18:19], v[40:41], v[26:27]
	s_waitcnt lgkmcnt(0)
	v_pk_fma_f32 v[36:37], v[22:23], v[14:15], v[36:37]
	v_pk_fma_f32 v[38:39], v[24:25], v[16:17], v[38:39]
	ds_read_b128 v[14:17], v1 offset:432
	ds_read_b128 v[18:21], v31 offset:56576
	ds_read_b128 v[22:25], v31 offset:56592
	s_waitcnt lgkmcnt(2)
	v_lshlrev_b32_e32 v40, 16, v14
	v_and_b32_e32 v41, 0xffff0000, v14
	v_lshlrev_b32_e32 v14, 16, v15
	v_and_b32_e32 v15, 0xffff0000, v15
	s_waitcnt lgkmcnt(1)
	v_pk_fma_f32 v[20:21], v[20:21], v[14:15], v[28:29]
	v_pk_fma_f32 v[14:15], v[18:19], v[40:41], v[26:27]
	v_lshlrev_b32_e32 v18, 16, v16
	v_bfe_u32 v1, v14, 16, 1
	v_add3_u32 v1, v14, v1, s33
	v_bfe_u32 v14, v15, 16, 1
	v_lshrrev_b32_e32 v1, 16, v1
	v_add3_u32 v14, v15, v14, s33
	v_and_or_b32 v14, v14, s11, v1
	v_and_b32_e32 v19, 0xffff0000, v16
	v_lshlrev_b32_e32 v16, 16, v17
	v_and_b32_e32 v17, 0xffff0000, v17
	s_waitcnt lgkmcnt(0)
	v_pk_fma_f32 v[24:25], v[24:25], v[16:17], v[38:39]
	v_pk_fma_f32 v[16:17], v[22:23], v[18:19], v[36:37]
	v_cvt_pk_bf16_f32 v15, v20, v21
	v_bfe_u32 v1, v16, 16, 1
	v_add3_u32 v1, v16, v1, s33
	v_bfe_u32 v16, v17, 16, 1
	v_lshrrev_b32_e32 v1, 16, v1
	v_add3_u32 v16, v17, v16, s33
	v_and_or_b32 v16, v16, s11, v1
	v_bfe_u32 v1, v24, 16, 1
	v_bfe_u32 v17, v25, 16, 1
	v_add3_u32 v1, v24, v1, s33
	v_add3_u32 v17, v25, v17, s33
	ds_read_b128 v[18:21], v31 offset:56960
	ds_read_b128 v[22:25], v31 offset:56976
	ds_read_b128 v[26:29], v198
	ds_read_b128 v[36:39], v31 offset:55936
	ds_read_b128 v[40:43], v31 offset:55952
	v_lshrrev_b32_e32 v1, 16, v1
	v_and_or_b32 v17, v17, s11, v1
	s_waitcnt lgkmcnt(2)
	v_lshlrev_b32_e32 v44, 16, v26
	v_and_b32_e32 v45, 0xffff0000, v26
	v_lshlrev_b32_e32 v26, 16, v27
	v_and_b32_e32 v27, 0xffff0000, v27
	s_waitcnt lgkmcnt(1)
	v_pk_fma_f32 v[38:39], v[38:39], v[26:27], v[20:21]
	v_pk_fma_f32 v[36:37], v[36:37], v[44:45], v[18:19]
	v_lshlrev_b32_e32 v18, 16, v28
	v_and_b32_e32 v19, 0xffff0000, v28
	v_lshlrev_b32_e32 v20, 16, v29
	v_and_b32_e32 v21, 0xffff0000, v29
	s_waitcnt lgkmcnt(0)
	v_pk_fma_f32 v[42:43], v[42:43], v[20:21], v[24:25]
	v_pk_fma_f32 v[40:41], v[40:41], v[18:19], v[22:23]
	ds_read_b128 v[18:21], v198 offset:144
	ds_read_b128 v[22:25], v31 offset:56192
	ds_read_b128 v[26:29], v31 offset:56208
	s_waitcnt lgkmcnt(2)
	v_lshlrev_b32_e32 v44, 16, v18
	v_and_b32_e32 v45, 0xffff0000, v18
	v_lshlrev_b32_e32 v18, 16, v19
	v_and_b32_e32 v19, 0xffff0000, v19
	s_waitcnt lgkmcnt(1)
	v_pk_fma_f32 v[38:39], v[24:25], v[18:19], v[38:39]
	v_lshlrev_b32_e32 v18, 16, v20
	v_and_b32_e32 v19, 0xffff0000, v20
	v_lshlrev_b32_e32 v20, 16, v21
	v_and_b32_e32 v21, 0xffff0000, v21
	v_pk_fma_f32 v[36:37], v[22:23], v[44:45], v[36:37]
	s_waitcnt lgkmcnt(0)
	v_pk_fma_f32 v[42:43], v[28:29], v[20:21], v[42:43]
	v_pk_fma_f32 v[40:41], v[26:27], v[18:19], v[40:41]
	ds_read_b128 v[18:21], v198 offset:288
	ds_read_b128 v[22:25], v31 offset:56448
	ds_read_b128 v[26:29], v31 offset:56464
	s_waitcnt lgkmcnt(2)
	v_lshlrev_b32_e32 v44, 16, v18
	v_and_b32_e32 v45, 0xffff0000, v18
	v_lshlrev_b32_e32 v18, 16, v19
	v_and_b32_e32 v19, 0xffff0000, v19
	s_waitcnt lgkmcnt(1)
	v_pk_fma_f32 v[38:39], v[24:25], v[18:19], v[38:39]
	v_lshlrev_b32_e32 v18, 16, v20
	v_and_b32_e32 v19, 0xffff0000, v20
	v_lshlrev_b32_e32 v20, 16, v21
	v_and_b32_e32 v21, 0xffff0000, v21
	v_pk_fma_f32 v[36:37], v[22:23], v[44:45], v[36:37]
	s_waitcnt lgkmcnt(0)
	v_pk_fma_f32 v[42:43], v[28:29], v[20:21], v[42:43]
	v_pk_fma_f32 v[40:41], v[26:27], v[18:19], v[40:41]
	ds_read_b128 v[18:21], v198 offset:432
	ds_read_b128 v[22:25], v31 offset:56704
	ds_read_b128 v[26:29], v31 offset:56720
	s_waitcnt lgkmcnt(2)
; #define LAS __attribute__((address_space(3)))
; __device__ __forceinline__ unsigned pk2(float lo, float hi) { return f2bf(lo) | (f2bf(hi) << 16); }
; template <bool PHASE_B>
; __device__ __forceinline__ void lru_item(const Params& p, LAS unsigned char* lds, int ci, int ci_next, int jb, const int tid, v4u (&xvn)[3]) {
;     ...
;     for (int ks = 0; ks < 2; ++ks) { const int cb0 = 32 * ks + 8 * fq;
;         f32x4 s0 = *(const LAS f32x4*)(CB + cb0), s1 = *(const LAS f32x4*)(CB + cb0 + 4);
; #pragma unroll
;         for (int tap = 0; tap < 4; ++tap) { const v4u v = *(const LAS v4u*)(lds + LR_XR + (16 * rt + fr + tap) * 144 + cb0 * 2);
;             const f32x4 w0 = *(const LAS f32x4*)(CW + tap * 64 + cb0), w1 = *(const LAS f32x4*)(CW + tap * 64 + cb0 + 4);
;             s0 += (f32x4){bflo(v.x), bfhi(v.x), bflo(v.y), bfhi(v.y)} * w0; s1 += (f32x4){bflo(v.z), bfhi(v.z), bflo(v.w), bfhi(v.w)} * w1; }
;         v4u o; o.x = pk2(s0[0], s0[1]); o.y = pk2(s0[2], s0[3]); o.z = pk2(s1[0], s1[1]); o.w = pk2(s1[2], s1[3]);
;         af[ks] = __builtin_bit_cast(bf16x8, o); }
;     float xc[4][4];
; #pragma unroll
;     for (int ct = 0; ct < 4; ++ct) { const int ch = 16 * ct + fr; float xr7[7];
; #pragma unroll
;         for (int j = 0; j < 7; ++j) xr7[j] = __builtin_bit_cast(float, (unsigned)(*(const LAS bf16*)(lds + LR_XR + (16 * rt + 4 * fq + j) * 144 + ch * 2)) << 16);
;         const float w0 = CW[ch], w1 = CW[64 + ch], w2 = CW[128 + ch], w3 = CW[192 + ch], b = CB[ch];
; #pragma unroll
;         for (int e = 0; e < 4; ++e) xc[ct][e] = b + xr7[e] * w0 + xr7[e + 1] * w1 + xr7[e + 2] * w2 + xr7[e + 3] * w3; }
	v_lshlrev_b32_e32 v44, 16, v18
	v_and_b32_e32 v45, 0xffff0000, v18
	v_lshlrev_b32_e32 v18, 16, v19
	v_and_b32_e32 v19, 0xffff0000, v19
	s_waitcnt lgkmcnt(1)
	v_pk_fma_f32 v[24:25], v[24:25], v[18:19], v[38:39]
	v_pk_fma_f32 v[18:19], v[22:23], v[44:45], v[36:37]
	v_lshlrev_b32_e32 v22, 16, v20
	v_bfe_u32 v1, v18, 16, 1
	v_add3_u32 v1, v18, v1, s33
	v_bfe_u32 v18, v19, 16, 1
	v_lshrrev_b32_e32 v1, 16, v1
	v_add3_u32 v18, v19, v18, s33
	v_and_or_b32 v18, v18, s11, v1
	v_and_b32_e32 v23, 0xffff0000, v20
	v_lshlrev_b32_e32 v20, 16, v21
	v_and_b32_e32 v21, 0xffff0000, v21
	s_waitcnt lgkmcnt(0)
	v_add_u32_e32 v249, v168, v169
	ds_read_u16 v249, v249
	v_pk_fma_f32 v[28:29], v[28:29], v[20:21], v[42:43]
	v_pk_fma_f32 v[20:21], v[26:27], v[22:23], v[40:41]
	v_cvt_pk_bf16_f32 v19, v24, v25
	v_bfe_u32 v1, v20, 16, 1
	v_add3_u32 v1, v20, v1, s33
	v_bfe_u32 v20, v21, 16, 1
	v_lshrrev_b32_e32 v1, 16, v1
	v_add3_u32 v20, v21, v20, s33
	v_and_or_b32 v20, v20, s11, v1
	v_cvt_pk_bf16_f32 v21, v28, v29
	v_add_u32_e32 v1, v168, v169
	s_waitcnt lgkmcnt(0)
	v_lshlrev_b32_e32 v23, 16, v249
	ds_read_u16 v22, v1 offset:144
	ds_read_u16 v31, v1 offset:288
	ds_read_u16 v38, v1 offset:432
	ds_read_u16 v39, v1 offset:576
	ds_read_u16 v46, v1 offset:720
	ds_read_u16 v1, v1 offset:864
	ds_read2_b32 v[24:25], v50 offset0:128 offset1:144
	ds_read2_b32 v[26:27], v50 offset0:192 offset1:208
	ds_read2_b32 v[28:29], v51 offset1:16
	ds_read2_b32 v[36:37], v51 offset0:64 offset1:80
	ds_read2_b32 v[40:41], v51 offset0:128 offset1:144
	s_waitcnt lgkmcnt(10)
	v_lshlrev_b32_e32 v45, 16, v22
	s_waitcnt lgkmcnt(8)
	v_lshlrev_b32_e32 v43, 16, v38
	s_waitcnt lgkmcnt(7)
	v_lshlrev_b32_e32 v42, 16, v39
	s_waitcnt lgkmcnt(3)
	v_mov_b32_e32 v38, v26
	v_mov_b32_e32 v39, v24
	v_mov_b32_e32 v22, v45
	v_pk_mul_f32 v[22:23], v[38:39], v[22:23]
	v_lshlrev_b32_e32 v44, 16, v31
	s_waitcnt lgkmcnt(0)
	ds_read_u16 v249, v199
	v_add_f32_e32 v23, v23, v40
	v_add_f32_e32 v24, v22, v23
	v_pk_mul_f32 v[22:23], v[38:39], v[44:45]
	v_mov_b32_e32 v47, v28
	v_add_f32_e32 v23, v23, v40
	v_add_f32_e32 v26, v22, v23
	v_pk_mov_b32 v[22:23], v[42:43], v[44:45] op_sel:[1,0]
	s_nop 0
	v_pk_mul_f32 v[44:45], v[38:39], v[22:23]
	v_pk_mul_f32 v[38:39], v[38:39], v[42:43]
	v_add_f32_e32 v31, v45, v40
	v_lshlrev_b32_e32 v45, 16, v46
	v_mov_b32_e32 v46, v36
	v_pk_mul_f32 v[48:49], v[46:47], v[22:23]
	v_pk_mul_f32 v[22:23], v[46:47], v[42:43]
	v_add_f32_e32 v31, v44, v31
	v_lshlrev_b32_e32 v44, 16, v1
	v_add_f32_e32 v1, v23, v26
	v_add_f32_e32 v108, v22, v1
	v_pk_mov_b32 v[22:23], v[44:45], v[42:43] op_sel:[1,0]
	v_add_f32_e32 v39, v39, v40
	v_pk_mul_f32 v[22:23], v[46:47], v[22:23]
	v_add_f32_e32 v38, v38, v39
	v_add_f32_e32 v1, v23, v31
	v_add_f32_e32 v106, v22, v1
	v_pk_mul_f32 v[22:23], v[46:47], v[44:45]
	v_add_f32_e32 v39, v49, v24
	v_add_f32_e32 v1, v23, v38
	v_add_f32_e32 v101, v22, v1
	v_add_f32_e32 v110, v48, v39
	s_waitcnt lgkmcnt(0)
	v_lshlrev_b32_e32 v23, 16, v249
	ds_read_u16 v1, v199 offset:144
	ds_read_u16 v22, v199 offset:288
	ds_read_u16 v24, v199 offset:432
	ds_read_u16 v26, v199 offset:576
	ds_read_u16 v28, v199 offset:720
	ds_read_u16 v31, v199 offset:864
	s_waitcnt lgkmcnt(3)
	v_lshlrev_b32_e32 v43, 16, v24
	v_mov_b32_e32 v24, v27
	v_lshlrev_b32_e32 v27, 16, v1
	s_waitcnt lgkmcnt(2)
	v_lshlrev_b32_e32 v42, 16, v26
	v_lshlrev_b32_e32 v26, 16, v22
	v_mov_b32_e32 v22, v27
	v_pk_mul_f32 v[22:23], v[24:25], v[22:23]
	s_nop 0
	v_add_f32_e32 v1, v23, v41
	v_add_f32_e32 v1, v22, v1
	v_pk_mul_f32 v[22:23], v[24:25], v[26:27]
	s_nop 0
	v_add_f32_e32 v23, v23, v41
	v_add_f32_e32 v36, v22, v23
	v_pk_mov_b32 v[22:23], v[42:43], v[26:27] op_sel:[1,0]
	s_nop 0
	v_pk_mul_f32 v[26:27], v[24:25], v[22:23]
	v_pk_mul_f32 v[24:25], v[24:25], v[42:43]
	v_add_f32_e32 v27, v27, v41
	v_add_f32_e32 v25, v25, v41
	v_add_f32_e32 v26, v26, v27
	v_add_f32_e32 v27, v24, v25
	s_waitcnt lgkmcnt(1)
	v_lshlrev_b32_e32 v25, 16, v28
	v_mov_b32_e32 v28, v37
	v_pk_mul_f32 v[64:65], v[28:29], v[22:23]
	v_pk_mul_f32 v[22:23], v[28:29], v[42:43]
	s_waitcnt lgkmcnt(0)
	ds_read_u16 v249, v200
	v_lshlrev_b32_e32 v24, 16, v31
	v_add_f32_e32 v57, v65, v1
	v_add_f32_e32 v1, v23, v36
	v_add_f32_e32 v120, v22, v1
	v_pk_mov_b32 v[22:23], v[24:25], v[42:43] op_sel:[1,0]
	v_add_f32_e32 v122, v64, v57
	v_pk_mul_f32 v[22:23], v[28:29], v[22:23]
	s_nop 0
	v_add_f32_e32 v1, v23, v26
	v_add_f32_e32 v118, v22, v1
	v_pk_mul_f32 v[22:23], v[28:29], v[24:25]
	s_nop 0
	v_add_f32_e32 v1, v23, v27
	v_add_f32_e32 v113, v22, v1
	s_waitcnt lgkmcnt(0)
	v_lshlrev_b32_e32 v23, 16, v249
	ds_read_u16 v1, v200 offset:144
	ds_read_u16 v22, v200 offset:288
	ds_read_u16 v31, v200 offset:432
	ds_read_u16 v38, v200 offset:576
	ds_read_u16 v49, v200 offset:720
	ds_read_u16 v52, v200 offset:864
	ds_read2_b32 v[24:25], v50 offset0:160 offset1:176
	ds_read2_b32 v[26:27], v50 offset0:224 offset1:240
	ds_read2_b32 v[28:29], v51 offset0:32 offset1:48
	ds_read2_b32 v[36:37], v51 offset0:96 offset1:112
	ds_read2_b32 v[40:41], v51 offset0:160 offset1:176
	s_waitcnt lgkmcnt(10)
	v_lshlrev_b32_e32 v47, 16, v1
	s_waitcnt lgkmcnt(3)
	v_mov_b32_e32 v44, v26
	v_mov_b32_e32 v45, v24
	v_lshlrev_b32_e32 v46, 16, v22
	v_mov_b32_e32 v22, v47
	v_pk_mul_f32 v[22:23], v[44:45], v[22:23]
	v_lshlrev_b32_e32 v43, 16, v31
	s_waitcnt lgkmcnt(0)
; #define LAS __attribute__((address_space(3)))
; #define MFMA16(a, b, c) __builtin_amdgcn_mfma_f32_16x16x32_bf16(a, b, c, 0, 0, 0)
; template <bool PHASE_B>
; __device__ __forceinline__ void lru_item(const Params& p, LAS unsigned char* lds, int ci, int ci_next, int jb, const int tid, v4u (&xvn)[3]) {
;     ...
;     for (int ct = 0; ct < 4; ++ct) { const int ch = 16 * ct + fr; float xr7[7];
; #pragma unroll
;         for (int j = 0; j < 7; ++j) xr7[j] = __builtin_bit_cast(float, (unsigned)(*(const LAS bf16*)(lds + LR_XR + (16 * rt + 4 * fq + j) * 144 + ch * 2)) << 16);
;         const float w0 = CW[ch], w1 = CW[64 + ch], w2 = CW[128 + ch], w3 = CW[192 + ch], b = CB[ch];
; #pragma unroll
;         for (int e = 0; e < 4; ++e) xc[ct][e] = b + xr7[e] * w0 + xr7[e + 1] * w1 + xr7[e + 2] * w2 + xr7[e + 3] * w3; }
;     float av[2][4][4], uv[2][4][4], pA[2][4], pH[2][4];
; #pragma unroll
;     for (int dir = 0; dir < 2; ++dir) {
; #pragma unroll
;         for (int ct = 0; ct < 4; ++ct) {
;             f32x4 ga = (f32x4){0.f, 0.f, 0.f, 0.f}, gx = (f32x4){0.f, 0.f, 0.f, 0.f};
; #pragma unroll
;             for (int ks = 0; ks < 2; ++ks) {
;                 const bf16x8 wa = *(const LAS bf16x8*)(lds + LR_WG + ((dir * 2 + 0) * 64 + 16 * ct + fr) * 144 + (32 * ks + 8 * fq) * 2);
;                 const bf16x8 wx = *(const LAS bf16x8*)(lds + LR_WG + ((dir * 2 + 1) * 64 + 16 * ct + fr) * 144 + (32 * ks + 8 * fq) * 2);
;                 ga = MFMA16(af[ks], wa, ga); gx = MFMA16(af[ks], wx, gx); }
;             const int ch = 16 * ct + fr; const float bav = GC[(dir * 3 + 0) * 64 + ch], bxv = GC[(dir * 3 + 1) * 64 + ch], c8 = GC[(dir * 3 + 2) * 64 + ch];
;             float Al = 1.f, Hl = 0.f;
; #pragma unroll
;             for (int ee = 0; ee < 4; ++ee) { const int e = dir ? 3 - ee : ee;
;                 const float r = __builtin_amdgcn_rcpf(1.f + __expf(-(ga[e] + bav))), ig = __builtin_amdgcn_rcpf(1.f + __expf(-(gx[e] + bxv)));
;                 const float la = -c8 * r; const float a = __expf(la); const float u = __builtin_amdgcn_sqrtf((1.f - a) * (1.f + a)) * (ig * xc[ct][e]);
;                 av[dir][ct][e] = a; uv[dir][ct][e] = u; Hl = a * Hl + u; Al *= a; }
	ds_read_u16 v249, v201
	v_add_f32_e32 v1, v23, v40
	v_add_f32_e32 v1, v22, v1
	v_pk_mul_f32 v[22:23], v[44:45], v[46:47]
	v_lshlrev_b32_e32 v42, 16, v38
	v_add_f32_e32 v23, v23, v40
	v_add_f32_e32 v24, v22, v23
	v_pk_mov_b32 v[22:23], v[42:43], v[46:47] op_sel:[1,0]
	v_mov_b32_e32 v50, v36
	v_pk_mul_f32 v[46:47], v[44:45], v[22:23]
	v_pk_mul_f32 v[44:45], v[44:45], v[42:43]
	v_mov_b32_e32 v51, v28
	v_add_f32_e32 v31, v45, v40
	v_add_f32_e32 v26, v47, v40
	v_add_f32_e32 v31, v44, v31
	v_pk_mul_f32 v[44:45], v[50:51], v[22:23]
	v_pk_mul_f32 v[22:23], v[50:51], v[42:43]
	v_add_f32_e32 v26, v46, v26
	v_lshlrev_b32_e32 v47, 16, v49
	v_lshlrev_b32_e32 v46, 16, v52
	v_add_f32_e32 v45, v45, v1
	v_add_f32_e32 v1, v23, v24
	v_add_f32_e32 v130, v22, v1
	v_pk_mov_b32 v[22:23], v[46:47], v[42:43] op_sel:[1,0]
	s_nop 0
	v_pk_mul_f32 v[22:23], v[50:51], v[22:23]
	s_nop 0
	v_add_f32_e32 v1, v23, v26
	v_add_f32_e32 v128, v22, v1
	v_pk_mul_f32 v[22:23], v[50:51], v[46:47]
	s_nop 0
	v_add_f32_e32 v1, v23, v31
	v_add_f32_e32 v125, v22, v1
	s_waitcnt lgkmcnt(0)
	v_lshlrev_b32_e32 v23, 16, v249
	ds_read_u16 v1, v201 offset:144
	ds_read_u16 v22, v201 offset:288
	ds_read_u16 v24, v201 offset:432
	ds_read_u16 v26, v201 offset:576
	ds_read_u16 v28, v201 offset:720
	ds_read_u16 v31, v201 offset:864
	s_waitcnt lgkmcnt(3)
	v_lshlrev_b32_e32 v43, 16, v24
	v_mov_b32_e32 v24, v27
	v_lshlrev_b32_e32 v27, 16, v1
	s_waitcnt lgkmcnt(2)
	v_lshlrev_b32_e32 v42, 16, v26
	v_lshlrev_b32_e32 v26, 16, v22
	v_mov_b32_e32 v22, v27
	v_pk_mul_f32 v[22:23], v[24:25], v[22:23]
	s_nop 0
	v_add_f32_e32 v1, v23, v41
	v_add_f32_e32 v1, v22, v1
	v_pk_mul_f32 v[22:23], v[24:25], v[26:27]
	s_nop 0
	v_add_f32_e32 v23, v23, v41
	v_add_f32_e32 v38, v22, v23
	v_pk_mov_b32 v[22:23], v[42:43], v[26:27] op_sel:[1,0]
	s_nop 0
	v_pk_mul_f32 v[26:27], v[24:25], v[22:23]
	v_pk_mul_f32 v[24:25], v[24:25], v[42:43]
	v_add_f32_e32 v27, v27, v41
	v_add_f32_e32 v25, v25, v41
	v_add_f32_e32 v26, v26, v27
	v_add_f32_e32 v27, v24, v25
	s_waitcnt lgkmcnt(1)
	v_lshlrev_b32_e32 v25, 16, v28
	v_mov_b32_e32 v28, v37
	v_pk_mul_f32 v[36:37], v[28:29], v[22:23]
	v_pk_mul_f32 v[22:23], v[28:29], v[42:43]
	s_waitcnt lgkmcnt(0)
	v_lshlrev_b32_e32 v24, 16, v31
	v_add_f32_e32 v37, v37, v1
	v_add_f32_e32 v1, v23, v38
	v_add_f32_e32 v31, v22, v1
	v_pk_mov_b32 v[22:23], v[24:25], v[42:43] op_sel:[1,0]
	s_nop 0
	v_pk_mul_f32 v[22:23], v[28:29], v[22:23]
	s_nop 0
	v_add_f32_e32 v1, v23, v26
	v_add_f32_e32 v136, v22, v1
	v_pk_mul_f32 v[22:23], v[28:29], v[24:25]
	s_nop 0
	v_add_f32_e32 v1, v23, v27
	v_add_f32_e32 v133, v22, v1
	ds_read_b128 v[22:25], v132 offset:18944
	ds_read_b128 v[26:29], v132 offset:28160
	s_waitcnt lgkmcnt(1)
	v_mfma_f32_16x16x32_bf16 v[22:25], v[14:17], v[22:25], 0
	s_waitcnt lgkmcnt(0)
	v_mfma_f32_16x16x32_bf16 v[40:43], v[14:17], v[26:29], 0
	ds_read_b128 v[26:29], v132 offset:19008
	ds_read_b128 v[50:53], v132 offset:28224
	ds_read_b32 v49, v174 offset:57088
	ds_read_b32 v47, v174 offset:57344
	ds_read_b32 v46, v174 offset:57600
	s_waitcnt lgkmcnt(4)
	v_mfma_f32_16x16x32_bf16 v[26:29], v[18:21], v[26:29], v[22:25]
	s_waitcnt lgkmcnt(3)
	v_mfma_f32_16x16x32_bf16 v[22:25], v[18:21], v[50:53], v[40:43]
	ds_read_b32 v227, v174 offset:57152
	ds_read_b32 v228, v174 offset:57408
	ds_read_b32 v229, v174 offset:57664
	ds_read_b128 v[208:211], v132 offset:21248
	ds_read_b128 v[212:215], v132 offset:30464
	ds_read_b128 v[216:219], v132 offset:21312
	ds_read_b128 v[220:223], v132 offset:30528
	s_waitcnt lgkmcnt(2)
	s_nop 4
	v_add_f32_e32 v1, v26, v49
	v_mul_f32_e32 v1, 0xbfb8aa3b, v1
	v_exp_f32_e32 v1, v1
	s_nop 0
	v_add_f32_e32 v1, 1.0, v1
	v_rcp_f32_e32 v1, v1
	s_waitcnt lgkmcnt(1)
	v_add_f32_e32 v22, v22, v47
	v_mul_f32_e32 v22, 0xbfb8aa3b, v22
	v_exp_f32_e32 v22, v22
	s_waitcnt lgkmcnt(0)
	v_mul_f32_e32 v1, v1, v46
	v_mul_f32_e32 v1, 0xbfb8aa3b, v1
	v_exp_f32_e32 v38, v1
	v_add_f32_e32 v22, 1.0, v22
	v_rcp_f32_e32 v50, v22
	v_add_f32_e32 v23, v23, v47
	v_sub_f32_e32 v1, 1.0, v38
	v_add_f32_e32 v22, 1.0, v38
	v_mul_f32_e32 v1, v1, v22
	v_add_f32_e32 v22, v27, v49
	v_mul_f32_e32 v22, 0xbfb8aa3b, v22
	v_exp_f32_e32 v22, v22
	v_mul_f32_e32 v23, 0xbfb8aa3b, v23
	v_exp_f32_e32 v23, v23
	v_add_f32_e32 v24, v24, v47
	v_add_f32_e32 v22, 1.0, v22
	v_rcp_f32_e32 v22, v22
	v_add_f32_e32 v23, 1.0, v23
	v_rcp_f32_e32 v23, v23
	v_add_f32_e32 v25, v25, v47
	v_mul_f32_e32 v22, v22, v46
	v_mul_f32_e32 v22, 0xbfb8aa3b, v22
	v_exp_f32_e32 v41, v22
	v_mul_f32_e32 v24, 0xbfb8aa3b, v24
	v_mul_f32_e32 v25, 0xbfb8aa3b, v25
	v_sqrt_f32_e32 v1, v1
	v_sub_f32_e32 v22, 1.0, v41
	v_add_f32_e32 v26, 1.0, v41
	v_mul_f32_e32 v22, v22, v26
	v_add_f32_e32 v26, v28, v49
	v_mul_f32_e32 v26, 0xbfb8aa3b, v26
	v_exp_f32_e32 v26, v26
	v_sqrt_f32_e32 v40, v22
	v_mul_f32_e32 v22, v108, v23
	v_mul_f32_e32 v23, v38, v41
	v_add_f32_e32 v26, 1.0, v26
	v_rcp_f32_e32 v26, v26
	v_exp_f32_e32 v24, v24
	v_exp_f32_e32 v25, v25
	v_mul_f32_e32 v39, v110, v50
	v_mul_f32_e32 v26, v26, v46
	v_mul_f32_e32 v26, 0xbfb8aa3b, v26
	v_exp_f32_e32 v43, v26
	v_add_f32_e32 v24, 1.0, v24
	v_add_f32_e32 v25, 1.0, v25
	v_rcp_f32_e32 v24, v24
	v_sub_f32_e32 v26, 1.0, v43
	v_add_f32_e32 v27, 1.0, v43
	v_mul_f32_e32 v26, v26, v27
	v_sqrt_f32_e32 v42, v26
	v_add_f32_e32 v26, v29, v49
	v_mul_f32_e32 v26, 0xbfb8aa3b, v26
	v_exp_f32_e32 v26, v26
	v_mul_f32_e32 v23, v43, v23
	v_pk_mul_f32 v[48:49], v[38:39], v[0:1]
	v_rcp_f32_e32 v25, v25
	v_add_f32_e32 v26, 1.0, v26
	v_rcp_f32_e32 v26, v26
	v_pk_fma_f32 v[50:51], v[38:39], v[0:1], v[48:49] op_sel_hi:[1,1,0]
	v_mul_f32_e32 v24, v106, v24
	v_mul_f32_e32 v26, v26, v46
	v_mul_f32_e32 v26, 0xbfb8aa3b, v26
	v_exp_f32_e32 v47, v26
	s_nop 0
	v_mul_f32_e32 v29, v47, v23
	ds_bpermute_b32 v56, v171, v29
	v_sub_f32_e32 v26, 1.0, v47
	v_add_f32_e32 v27, 1.0, v47
	v_mul_f32_e32 v26, v26, v27
	v_sqrt_f32_e32 v46, v26
	s_waitcnt lgkmcnt(0)
; #define LAS __attribute__((address_space(3)))
; #define MFMA16(a, b, c) __builtin_amdgcn_mfma_f32_16x16x32_bf16(a, b, c, 0, 0, 0)
; template <bool PHASE_B>
; __device__ __forceinline__ void lru_item(const Params& p, LAS unsigned char* lds, int ci, int ci_next, int jb, const int tid, v4u (&xvn)[3]) {
;     ...
;                 const bf16x8 wa = *(const LAS bf16x8*)(lds + LR_WG + ((dir * 2 + 0) * 64 + 16 * ct + fr) * 144 + (32 * ks + 8 * fq) * 2);
;                 const bf16x8 wx = *(const LAS bf16x8*)(lds + LR_WG + ((dir * 2 + 1) * 64 + 16 * ct + fr) * 144 + (32 * ks + 8 * fq) * 2);
;                 ga = MFMA16(af[ks], wa, ga); gx = MFMA16(af[ks], wx, gx); }
;             const int ch = 16 * ct + fr; const float bav = GC[(dir * 3 + 0) * 64 + ch], bxv = GC[(dir * 3 + 1) * 64 + ch], c8 = GC[(dir * 3 + 2) * 64 + ch];
;             float Al = 1.f, Hl = 0.f;
; #pragma unroll
;             for (int ee = 0; ee < 4; ++ee) { const int e = dir ? 3 - ee : ee;
;                 const float r = __builtin_amdgcn_rcpf(1.f + __expf(-(ga[e] + bav))), ig = __builtin_amdgcn_rcpf(1.f + __expf(-(gx[e] + bxv)));
;                 const float la = -c8 * r; const float a = __expf(la); const float u = __builtin_amdgcn_sqrtf((1.f - a) * (1.f + a)) * (ig * xc[ct][e]);
;                 av[dir][ct][e] = a; uv[dir][ct][e] = u; Hl = a * Hl + u; Al *= a; }
;             const int o = dir ? 3 - fq : fq; const bool odd = (o & 1) != 0, hi2 = (o & 2) != 0;
;             const float A1 = __shfl_xor(Al, 16), H1 = __shfl_xor(Hl, 16);
;             const float pxA = odd ? A1 : 1.f, pxH = odd ? H1 : 0.f;
;             const float gA = Al * A1, gH = odd ? (Al * H1 + Hl) : (A1 * Hl + H1);
;             const float A2 = __shfl_xor(gA, 32), H2 = __shfl_xor(gH, 32);
;             const float PA = hi2 ? pxA * A2 : pxA, PH = hi2 ? (pxA * H2 + pxH) : pxH;
;             const float TA = gA * A2, TH = hi2 ? (gA * H2 + gH) : (A2 * gH + H2);
;             pA[dir][ct] = PA; pH[dir][ct] = PH;
;             ((LAS f32x2*)(lds + LR_SEG))[(dir * 8 + rt) * 64 + ch] = (f32x2){TA, TH};
	v_mul_f32_e32 v59, v29, v56
	ds_bpermute_b32 v60, v172, v59
	v_cndmask_b32_e64 v58, v56, 1.0, s[50:51]
	v_mul_f32_e32 v26, v101, v25
	s_waitcnt lgkmcnt(0)
	v_mul_f32_e32 v23, v58, v60
	v_cndmask_b32_e64 v206, v23, v58, s[52:53]
	v_mov_b32_e32 v23, v51
	v_pk_mul_f32 v[50:51], v[22:23], v[40:41]
	v_mul_f32_e32 v28, v59, v60
	v_pk_fma_f32 v[22:23], v[22:23], v[40:41], v[50:51] op_sel_hi:[1,1,0]
	s_nop 0
	v_mov_b32_e32 v25, v23
	v_pk_mul_f32 v[52:53], v[24:25], v[42:43]
	s_nop 0
	v_pk_fma_f32 v[22:23], v[24:25], v[42:43], v[52:53] op_sel_hi:[1,1,0]
	s_nop 0
	v_mov_b32_e32 v27, v23
	v_pk_mul_f32 v[54:55], v[26:27], v[46:47]
	s_nop 0
	v_add_f32_e32 v1, v54, v55
	ds_bpermute_b32 v22, v171, v1
	s_waitcnt lgkmcnt(0)
	v_cndmask_b32_e64 v23, v22, 0, s[50:51]
	v_fma_f32 v24, v29, v22, v1
	v_fmac_f32_e32 v22, v1, v56
	v_cndmask_b32_e64 v1, v24, v22, s[50:51]
	ds_bpermute_b32 v22, v172, v1
	s_waitcnt lgkmcnt(0)
	v_fma_f32 v24, v58, v22, v23
	v_cndmask_b32_e64 v39, v24, v23, s[52:53]
	v_fma_f32 v23, v59, v22, v1
	v_fmac_f32_e32 v22, v1, v60
	v_cndmask_b32_e64 v29, v23, v22, s[52:53]
	ds_write_b64 v175, v[28:29] offset:58624
	s_waitcnt lgkmcnt(1)
	v_mfma_f32_16x16x32_bf16 v[22:25], v[14:17], v[208:211], 0
	s_waitcnt lgkmcnt(0)
	v_mfma_f32_16x16x32_bf16 v[58:61], v[14:17], v[212:215], 0
	s_waitcnt lgkmcnt(4)
	v_mfma_f32_16x16x32_bf16 v[26:29], v[18:21], v[216:219], v[22:25]
	s_waitcnt lgkmcnt(3)
	v_mfma_f32_16x16x32_bf16 v[22:25], v[18:21], v[220:223], v[58:61]
	ds_read_b128 v[208:211], v132 offset:23552
	ds_read_b128 v[212:215], v132 offset:32768
	ds_read_b128 v[216:219], v132 offset:23616
	ds_read_b128 v[220:223], v132 offset:32832
	s_waitcnt lgkmcnt(2)
	s_nop 4
	v_add_f32_e32 v1, v26, v227
	v_mul_f32_e32 v1, 0xbfb8aa3b, v1
	v_exp_f32_e32 v1, v1
	s_nop 0
	v_add_f32_e32 v1, 1.0, v1
	v_rcp_f32_e32 v1, v1
	s_waitcnt lgkmcnt(1)
	v_add_f32_e32 v22, v22, v228
	v_mul_f32_e32 v22, 0xbfb8aa3b, v22
	v_exp_f32_e32 v22, v22
	s_waitcnt lgkmcnt(0)
	v_mul_f32_e32 v1, v1, v229
	v_mul_f32_e32 v1, 0xbfb8aa3b, v1
	v_exp_f32_e32 v56, v1
	v_add_f32_e32 v22, 1.0, v22
	v_rcp_f32_e32 v48, v22
	v_add_f32_e32 v23, v23, v228
	v_sub_f32_e32 v1, 1.0, v56
	v_add_f32_e32 v22, 1.0, v56
	v_mul_f32_e32 v1, v1, v22
	v_add_f32_e32 v22, v27, v227
	v_mul_f32_e32 v22, 0xbfb8aa3b, v22
	v_exp_f32_e32 v22, v22
	v_mul_f32_e32 v23, 0xbfb8aa3b, v23
	v_exp_f32_e32 v23, v23
	v_add_f32_e32 v24, v24, v228
	v_add_f32_e32 v22, 1.0, v22
	v_rcp_f32_e32 v22, v22
	v_add_f32_e32 v23, 1.0, v23
	v_rcp_f32_e32 v23, v23
	v_add_f32_e32 v25, v25, v228
	v_mul_f32_e32 v22, v22, v229
	v_mul_f32_e32 v22, 0xbfb8aa3b, v22
	v_exp_f32_e32 v59, v22
	v_mul_f32_e32 v24, 0xbfb8aa3b, v24
	v_mul_f32_e32 v25, 0xbfb8aa3b, v25
	v_sqrt_f32_e32 v1, v1
	v_sub_f32_e32 v22, 1.0, v59
	v_add_f32_e32 v26, 1.0, v59
	v_mul_f32_e32 v22, v22, v26
	v_add_f32_e32 v26, v28, v227
	v_mul_f32_e32 v26, 0xbfb8aa3b, v26
	v_exp_f32_e32 v26, v26
	v_sqrt_f32_e32 v58, v22
	v_mul_f32_e32 v22, v120, v23
	v_mul_f32_e32 v23, v56, v59
	v_add_f32_e32 v26, 1.0, v26
	v_rcp_f32_e32 v26, v26
	v_exp_f32_e32 v24, v24
	v_exp_f32_e32 v25, v25
	v_mul_f32_e32 v57, v122, v48
	v_mul_f32_e32 v26, v26, v229
	v_mul_f32_e32 v26, 0xbfb8aa3b, v26
	v_exp_f32_e32 v61, v26
	v_add_f32_e32 v24, 1.0, v24
	v_add_f32_e32 v25, 1.0, v25
	v_pk_mul_f32 v[64:65], v[56:57], v[0:1]
	v_sub_f32_e32 v26, 1.0, v61
	v_add_f32_e32 v27, 1.0, v61
	v_mul_f32_e32 v26, v26, v27
	v_sqrt_f32_e32 v60, v26
	v_add_f32_e32 v26, v29, v227
	v_mul_f32_e32 v26, 0xbfb8aa3b, v26
	v_exp_f32_e32 v26, v26
	v_mul_f32_e32 v23, v61, v23
	v_rcp_f32_e32 v24, v24
	v_rcp_f32_e32 v25, v25
	v_add_f32_e32 v26, 1.0, v26
	v_rcp_f32_e32 v26, v26
	v_pk_fma_f32 v[66:67], v[56:57], v[0:1], v[64:65] op_sel_hi:[1,1,0]
	v_mul_f32_e32 v24, v118, v24
	v_mul_f32_e32 v26, v26, v229
	v_mul_f32_e32 v26, 0xbfb8aa3b, v26
	v_exp_f32_e32 v63, v26
	s_nop 0
	v_mul_f32_e32 v29, v63, v23
	ds_bpermute_b32 v42, v171, v29
	v_sub_f32_e32 v26, 1.0, v63
	v_add_f32_e32 v27, 1.0, v63
	v_mul_f32_e32 v26, v26, v27
	v_sqrt_f32_e32 v62, v26
	s_waitcnt lgkmcnt(0)
	v_mul_f32_e32 v51, v29, v42
	ds_bpermute_b32 v53, v172, v51
	v_cndmask_b32_e64 v46, v42, 1.0, s[50:51]
	v_mul_f32_e32 v26, v113, v25
	s_waitcnt lgkmcnt(0)
	v_mul_f32_e32 v23, v46, v53
	v_cndmask_b32_e64 v40, v23, v46, s[52:53]
	v_mov_b32_e32 v23, v67
	v_pk_mul_f32 v[66:67], v[22:23], v[58:59]
	v_mul_f32_e32 v28, v51, v53
	v_pk_fma_f32 v[22:23], v[22:23], v[58:59], v[66:67] op_sel_hi:[1,1,0]
	s_nop 0
	v_mov_b32_e32 v25, v23
	v_pk_mul_f32 v[68:69], v[24:25], v[60:61]
	s_nop 0
	v_pk_fma_f32 v[22:23], v[24:25], v[60:61], v[68:69] op_sel_hi:[1,1,0]
	v_add_f32_e32 v69, v44, v45
	v_mov_b32_e32 v27, v23
	v_pk_mul_f32 v[70:71], v[26:27], v[62:63]
	s_nop 0
	v_add_f32_e32 v1, v70, v71
	ds_bpermute_b32 v22, v171, v1
	v_add_f32_e32 v71, v36, v37
	s_waitcnt lgkmcnt(0)
	v_cndmask_b32_e64 v23, v22, 0, s[50:51]
	v_fma_f32 v24, v29, v22, v1
	v_fmac_f32_e32 v22, v1, v42
	v_cndmask_b32_e64 v1, v24, v22, s[50:51]
	ds_bpermute_b32 v22, v172, v1
	s_waitcnt lgkmcnt(0)
	v_fma_f32 v24, v46, v22, v23
	v_cndmask_b32_e64 v42, v24, v23, s[52:53]
	v_fma_f32 v23, v51, v22, v1
	v_fmac_f32_e32 v22, v1, v53
	v_cndmask_b32_e64 v29, v23, v22, s[52:53]
	ds_write_b64 v175, v[28:29] offset:58752
	s_waitcnt lgkmcnt(1)
	v_mfma_f32_16x16x32_bf16 v[22:25], v[14:17], v[208:211], 0
	s_waitcnt lgkmcnt(2)
	v_mfma_f32_16x16x32_bf16 v[26:29], v[14:17], v[212:215], 0
	s_waitcnt lgkmcnt(1)
	v_mfma_f32_16x16x32_bf16 v[80:83], v[18:21], v[216:219], v[22:25]
	s_waitcnt lgkmcnt(0)
; #define LAS __attribute__((address_space(3)))
; #define MFMA16(a, b, c) __builtin_amdgcn_mfma_f32_16x16x32_bf16(a, b, c, 0, 0, 0)
; template <bool PHASE_B>
; __device__ __forceinline__ void lru_item(const Params& p, LAS unsigned char* lds, int ci, int ci_next, int jb, const int tid, v4u (&xvn)[3]) {
;     ...
;                 const bf16x8 wa = *(const LAS bf16x8*)(lds + LR_WG + ((dir * 2 + 0) * 64 + 16 * ct + fr) * 144 + (32 * ks + 8 * fq) * 2);
;                 const bf16x8 wx = *(const LAS bf16x8*)(lds + LR_WG + ((dir * 2 + 1) * 64 + 16 * ct + fr) * 144 + (32 * ks + 8 * fq) * 2);
;                 ga = MFMA16(af[ks], wa, ga); gx = MFMA16(af[ks], wx, gx); }
;             const int ch = 16 * ct + fr; const float bav = GC[(dir * 3 + 0) * 64 + ch], bxv = GC[(dir * 3 + 1) * 64 + ch], c8 = GC[(dir * 3 + 2) * 64 + ch];
;             float Al = 1.f, Hl = 0.f;
; #pragma unroll
;             for (int ee = 0; ee < 4; ++ee) { const int e = dir ? 3 - ee : ee;
;                 const float r = __builtin_amdgcn_rcpf(1.f + __expf(-(ga[e] + bav))), ig = __builtin_amdgcn_rcpf(1.f + __expf(-(gx[e] + bxv)));
;                 const float la = -c8 * r; const float a = __expf(la); const float u = __builtin_amdgcn_sqrtf((1.f - a) * (1.f + a)) * (ig * xc[ct][e]);
;                 av[dir][ct][e] = a; uv[dir][ct][e] = u; Hl = a * Hl + u; Al *= a; }
;             const int o = dir ? 3 - fq : fq; const bool odd = (o & 1) != 0, hi2 = (o & 2) != 0;
;             const float A1 = __shfl_xor(Al, 16), H1 = __shfl_xor(Hl, 16);
;             const float pxA = odd ? A1 : 1.f, pxH = odd ? H1 : 0.f;
;             const float gA = Al * A1, gH = odd ? (Al * H1 + Hl) : (A1 * Hl + H1);
;             const float A2 = __shfl_xor(gA, 32), H2 = __shfl_xor(gH, 32);
;             const float PA = hi2 ? pxA * A2 : pxA, PH = hi2 ? (pxA * H2 + pxH) : pxH;
;             const float TA = gA * A2, TH = hi2 ? (gA * H2 + gH) : (A2 * gH + H2);
;             pA[dir][ct] = PA; pH[dir][ct] = PH;
;             ((LAS f32x2*)(lds + LR_SEG))[(dir * 8 + rt) * 64 + ch] = (f32x2){TA, TH};
	v_mfma_f32_16x16x32_bf16 v[22:25], v[18:21], v[220:223], v[26:29]
	ds_read_b32 v224, v174 offset:57216
	ds_read_b32 v225, v174 offset:57472
	ds_read_b32 v226, v174 offset:57728
	ds_read_b128 v[208:211], v132 offset:25856
	ds_read_b128 v[212:215], v132 offset:35072
	ds_read_b128 v[216:219], v132 offset:25920
	ds_read_b128 v[220:223], v132 offset:35136
	s_nop 3
	s_waitcnt lgkmcnt(2)
	v_add_f32_e32 v1, v80, v224
	v_mul_f32_e32 v1, 0xbfb8aa3b, v1
	v_exp_f32_e32 v1, v1
	s_waitcnt lgkmcnt(1)
	v_add_f32_e32 v22, v22, v225
	v_mul_f32_e32 v22, 0xbfb8aa3b, v22
	v_exp_f32_e32 v22, v22
	v_add_f32_e32 v1, 1.0, v1
	v_rcp_f32_e32 v1, v1
	v_add_f32_e32 v23, v23, v225
	v_add_f32_e32 v22, 1.0, v22
	v_rcp_f32_e32 v29, v22
	s_waitcnt lgkmcnt(0)
	v_mul_f32_e32 v1, v1, v226
	v_mul_f32_e32 v1, 0xbfb8aa3b, v1
	v_exp_f32_e32 v72, v1
	v_mul_f32_e32 v23, 0xbfb8aa3b, v23
	v_exp_f32_e32 v23, v23
	v_add_f32_e32 v24, v24, v225
	v_sub_f32_e32 v1, 1.0, v72
	v_add_f32_e32 v22, 1.0, v72
	v_mul_f32_e32 v1, v1, v22
	v_add_f32_e32 v22, v81, v224
	v_mul_f32_e32 v22, 0xbfb8aa3b, v22
	v_exp_f32_e32 v22, v22
	v_add_f32_e32 v23, 1.0, v23
	v_rcp_f32_e32 v23, v23
	v_add_f32_e32 v25, v25, v225
	v_add_f32_e32 v22, 1.0, v22
	v_rcp_f32_e32 v22, v22
	v_mul_f32_e32 v24, 0xbfb8aa3b, v24
	v_mul_f32_e32 v25, 0xbfb8aa3b, v25
	v_sqrt_f32_e32 v1, v1
	v_mul_f32_e32 v22, v22, v226
	v_mul_f32_e32 v22, 0xbfb8aa3b, v22
	v_exp_f32_e32 v75, v22
	v_exp_f32_e32 v24, v24
	v_exp_f32_e32 v25, v25
	v_mul_f32_e32 v73, v69, v29
	v_sub_f32_e32 v22, 1.0, v75
	v_add_f32_e32 v46, 1.0, v75
	v_mul_f32_e32 v22, v22, v46
	v_add_f32_e32 v46, v82, v224
	v_mul_f32_e32 v46, 0xbfb8aa3b, v46
	v_add_f32_e32 v26, v83, v224
	v_exp_f32_e32 v46, v46
	v_mul_f32_e32 v26, 0xbfb8aa3b, v26
	v_exp_f32_e32 v26, v26
	v_sqrt_f32_e32 v74, v22
	v_add_f32_e32 v46, 1.0, v46
	v_rcp_f32_e32 v46, v46
	v_add_f32_e32 v26, 1.0, v26
	v_rcp_f32_e32 v26, v26
	v_mul_f32_e32 v22, v130, v23
	v_mul_f32_e32 v46, v46, v226
	v_mul_f32_e32 v46, 0xbfb8aa3b, v46
	v_mul_f32_e32 v26, v26, v226
	v_exp_f32_e32 v77, v46
	v_mul_f32_e32 v26, 0xbfb8aa3b, v26
	v_exp_f32_e32 v79, v26
	v_mul_f32_e32 v23, v72, v75
	v_sub_f32_e32 v46, 1.0, v77
	v_add_f32_e32 v48, 1.0, v77
	v_mul_f32_e32 v23, v77, v23
	v_mul_f32_e32 v46, v46, v48
	v_mul_f32_e32 v48, v79, v23
	ds_bpermute_b32 v51, v171, v48
	v_add_f32_e32 v24, 1.0, v24
	v_add_f32_e32 v25, 1.0, v25
	v_pk_mul_f32 v[44:45], v[72:73], v[0:1]
	v_rcp_f32_e32 v24, v24
	s_waitcnt lgkmcnt(0)
	v_mul_f32_e32 v55, v48, v51
	ds_bpermute_b32 v57, v172, v55
	v_cndmask_b32_e64 v53, v51, 1.0, s[50:51]
	v_rcp_f32_e32 v25, v25
	v_pk_fma_f32 v[80:81], v[72:73], v[0:1], v[44:45] op_sel_hi:[1,1,0]
	v_sqrt_f32_e32 v76, v46
	s_waitcnt lgkmcnt(0)
	v_mul_f32_e32 v23, v53, v57
	v_cndmask_b32_e64 v46, v23, v53, s[52:53]
	v_mov_b32_e32 v23, v81
	v_sub_f32_e32 v26, 1.0, v79
	v_add_f32_e32 v27, 1.0, v79
	v_pk_mul_f32 v[80:81], v[22:23], v[74:75]
	v_mul_f32_e32 v26, v26, v27
	v_pk_fma_f32 v[22:23], v[22:23], v[74:75], v[80:81] op_sel_hi:[1,1,0]
	v_mul_f32_e32 v24, v128, v24
	v_sqrt_f32_e32 v78, v26
	v_mul_f32_e32 v26, v125, v25
	v_mov_b32_e32 v25, v23
	v_pk_mul_f32 v[82:83], v[24:25], v[76:77]
	v_mul_f32_e32 v28, v55, v57
	v_pk_fma_f32 v[22:23], v[24:25], v[76:77], v[82:83] op_sel_hi:[1,1,0]
	s_nop 0
	v_mov_b32_e32 v27, v23
	v_pk_mul_f32 v[84:85], v[26:27], v[78:79]
	s_nop 0
	v_add_f32_e32 v1, v84, v85
	ds_bpermute_b32 v22, v171, v1
	s_waitcnt lgkmcnt(0)
	v_cndmask_b32_e64 v23, v22, 0, s[50:51]
	v_fma_f32 v24, v48, v22, v1
	v_fmac_f32_e32 v22, v1, v51
	v_cndmask_b32_e64 v1, v24, v22, s[50:51]
	ds_bpermute_b32 v22, v172, v1
	s_waitcnt lgkmcnt(0)
	v_fma_f32 v24, v53, v22, v23
	v_cndmask_b32_e64 v44, v24, v23, s[52:53]
	v_fma_f32 v23, v55, v22, v1
	v_fmac_f32_e32 v22, v1, v57
	v_cndmask_b32_e64 v29, v23, v22, s[52:53]
	ds_write_b64 v175, v[28:29] offset:58880
	s_waitcnt lgkmcnt(1)
	v_mfma_f32_16x16x32_bf16 v[22:25], v[14:17], v[208:211], 0
	s_waitcnt lgkmcnt(2)
	v_mfma_f32_16x16x32_bf16 v[26:29], v[14:17], v[212:215], 0
	s_waitcnt lgkmcnt(1)
	v_mfma_f32_16x16x32_bf16 v[94:97], v[18:21], v[216:219], v[22:25]
	s_waitcnt lgkmcnt(0)
	v_mfma_f32_16x16x32_bf16 v[22:25], v[18:21], v[220:223], v[26:29]
	ds_read_b32 v227, v174 offset:57280
	ds_read_b32 v228, v174 offset:57536
	ds_read_b32 v229, v174 offset:57792
	ds_read_b128 v[208:211], v132 offset:37376
	ds_read_b128 v[212:215], v132 offset:46592
	ds_read_b128 v[216:219], v132 offset:37440
	ds_read_b128 v[220:223], v132 offset:46656
	s_nop 3
	s_waitcnt lgkmcnt(2)
	v_add_f32_e32 v1, v94, v227
	v_mul_f32_e32 v1, 0xbfb8aa3b, v1
	v_exp_f32_e32 v1, v1
	s_waitcnt lgkmcnt(1)
	v_add_f32_e32 v22, v22, v228
	v_mul_f32_e32 v22, 0xbfb8aa3b, v22
	v_exp_f32_e32 v22, v22
	v_add_f32_e32 v1, 1.0, v1
	v_rcp_f32_e32 v1, v1
	v_add_f32_e32 v23, v23, v228
	v_add_f32_e32 v22, 1.0, v22
	v_rcp_f32_e32 v29, v22
	s_waitcnt lgkmcnt(0)
; #define LAS __attribute__((address_space(3)))
; #define MFMA16(a, b, c) __builtin_amdgcn_mfma_f32_16x16x32_bf16(a, b, c, 0, 0, 0)
; template <bool PHASE_B>
; __device__ __forceinline__ void lru_item(const Params& p, LAS unsigned char* lds, int ci, int ci_next, int jb, const int tid, v4u (&xvn)[3]) {
;     ...
;                 const bf16x8 wa = *(const LAS bf16x8*)(lds + LR_WG + ((dir * 2 + 0) * 64 + 16 * ct + fr) * 144 + (32 * ks + 8 * fq) * 2);
;                 const bf16x8 wx = *(const LAS bf16x8*)(lds + LR_WG + ((dir * 2 + 1) * 64 + 16 * ct + fr) * 144 + (32 * ks + 8 * fq) * 2);
;                 ga = MFMA16(af[ks], wa, ga); gx = MFMA16(af[ks], wx, gx); }
;             const int ch = 16 * ct + fr; const float bav = GC[(dir * 3 + 0) * 64 + ch], bxv = GC[(dir * 3 + 1) * 64 + ch], c8 = GC[(dir * 3 + 2) * 64 + ch];
;             float Al = 1.f, Hl = 0.f;
; #pragma unroll
;             for (int ee = 0; ee < 4; ++ee) { const int e = dir ? 3 - ee : ee;
;                 const float r = __builtin_amdgcn_rcpf(1.f + __expf(-(ga[e] + bav))), ig = __builtin_amdgcn_rcpf(1.f + __expf(-(gx[e] + bxv)));
;                 const float la = -c8 * r; const float a = __expf(la); const float u = __builtin_amdgcn_sqrtf((1.f - a) * (1.f + a)) * (ig * xc[ct][e]);
;                 av[dir][ct][e] = a; uv[dir][ct][e] = u; Hl = a * Hl + u; Al *= a; }
;             const int o = dir ? 3 - fq : fq; const bool odd = (o & 1) != 0, hi2 = (o & 2) != 0;
;             const float A1 = __shfl_xor(Al, 16), H1 = __shfl_xor(Hl, 16);
;             const float pxA = odd ? A1 : 1.f, pxH = odd ? H1 : 0.f;
;             const float gA = Al * A1, gH = odd ? (Al * H1 + Hl) : (A1 * Hl + H1);
;             const float A2 = __shfl_xor(gA, 32), H2 = __shfl_xor(gH, 32);
;             const float PA = hi2 ? pxA * A2 : pxA, PH = hi2 ? (pxA * H2 + pxH) : pxH;
;             const float TA = gA * A2, TH = hi2 ? (gA * H2 + gH) : (A2 * gH + H2);
;             pA[dir][ct] = PA; pH[dir][ct] = PH;
;             ((LAS f32x2*)(lds + LR_SEG))[(dir * 8 + rt) * 64 + ch] = (f32x2){TA, TH};
	v_mul_f32_e32 v1, v1, v229
	v_mul_f32_e32 v1, 0xbfb8aa3b, v1
	v_exp_f32_e32 v86, v1
	v_mul_f32_e32 v23, 0xbfb8aa3b, v23
	v_exp_f32_e32 v23, v23
	v_add_f32_e32 v24, v24, v228
	v_sub_f32_e32 v1, 1.0, v86
	v_add_f32_e32 v22, 1.0, v86
	v_mul_f32_e32 v1, v1, v22
	v_add_f32_e32 v22, v95, v227
	v_mul_f32_e32 v22, 0xbfb8aa3b, v22
	v_exp_f32_e32 v22, v22
	v_add_f32_e32 v23, 1.0, v23
	v_rcp_f32_e32 v23, v23
	v_add_f32_e32 v25, v25, v228
	v_add_f32_e32 v22, 1.0, v22
	v_rcp_f32_e32 v22, v22
	v_mul_f32_e32 v24, 0xbfb8aa3b, v24
	v_mul_f32_e32 v25, 0xbfb8aa3b, v25
	v_sqrt_f32_e32 v1, v1
	v_mul_f32_e32 v22, v22, v229
	v_mul_f32_e32 v22, 0xbfb8aa3b, v22
	v_exp_f32_e32 v89, v22
	v_exp_f32_e32 v24, v24
	v_exp_f32_e32 v25, v25
	v_mul_f32_e32 v87, v71, v29
	v_sub_f32_e32 v22, 1.0, v89
	v_add_f32_e32 v48, 1.0, v89
	v_mul_f32_e32 v22, v22, v48
	v_add_f32_e32 v48, v96, v227
	v_mul_f32_e32 v48, 0xbfb8aa3b, v48
	v_add_f32_e32 v26, v97, v227
	v_exp_f32_e32 v48, v48
	v_mul_f32_e32 v26, 0xbfb8aa3b, v26
	v_exp_f32_e32 v26, v26
	v_sqrt_f32_e32 v88, v22
	v_add_f32_e32 v48, 1.0, v48
	v_rcp_f32_e32 v48, v48
	v_add_f32_e32 v26, 1.0, v26
	v_rcp_f32_e32 v26, v26
	v_mul_f32_e32 v22, v31, v23
	v_mul_f32_e32 v48, v48, v229
	v_mul_f32_e32 v48, 0xbfb8aa3b, v48
	v_mul_f32_e32 v26, v26, v229
	v_exp_f32_e32 v91, v48
	v_mul_f32_e32 v26, 0xbfb8aa3b, v26
	v_exp_f32_e32 v93, v26
	v_mul_f32_e32 v23, v86, v89
	v_sub_f32_e32 v48, 1.0, v91
	v_add_f32_e32 v51, 1.0, v91
	v_mul_f32_e32 v23, v91, v23
	v_mul_f32_e32 v48, v48, v51
	v_mul_f32_e32 v51, v93, v23
	ds_bpermute_b32 v53, v171, v51
	v_add_f32_e32 v24, 1.0, v24
	v_add_f32_e32 v25, 1.0, v25
	v_pk_mul_f32 v[36:37], v[86:87], v[0:1]
	v_rcp_f32_e32 v24, v24
	s_waitcnt lgkmcnt(0)
	v_mul_f32_e32 v57, v51, v53
	ds_bpermute_b32 v58, v172, v57
	v_cndmask_b32_e64 v55, v53, 1.0, s[50:51]
	v_rcp_f32_e32 v25, v25
	v_pk_fma_f32 v[94:95], v[86:87], v[0:1], v[36:37] op_sel_hi:[1,1,0]
	v_sqrt_f32_e32 v90, v48
	s_waitcnt lgkmcnt(0)
	v_mul_f32_e32 v23, v55, v58
	v_cndmask_b32_e64 v48, v23, v55, s[52:53]
	v_mov_b32_e32 v23, v95
	v_sub_f32_e32 v26, 1.0, v93
	v_add_f32_e32 v27, 1.0, v93
	v_pk_mul_f32 v[94:95], v[22:23], v[88:89]
	v_mul_f32_e32 v26, v26, v27
	v_pk_fma_f32 v[22:23], v[22:23], v[88:89], v[94:95] op_sel_hi:[1,1,0]
	v_mul_f32_e32 v24, v136, v24
	v_sqrt_f32_e32 v92, v26
	v_mul_f32_e32 v26, v133, v25
	v_mov_b32_e32 v25, v23
	v_pk_mul_f32 v[96:97], v[24:25], v[90:91]
	v_mul_f32_e32 v28, v57, v58
	v_pk_fma_f32 v[22:23], v[24:25], v[90:91], v[96:97] op_sel_hi:[1,1,0]
	s_nop 0
	v_mov_b32_e32 v27, v23
	v_pk_mul_f32 v[98:99], v[26:27], v[92:93]
	s_nop 0
	v_add_f32_e32 v1, v98, v99
	ds_bpermute_b32 v22, v171, v1
	s_waitcnt lgkmcnt(0)
	v_cndmask_b32_e64 v23, v22, 0, s[50:51]
	v_fma_f32 v24, v51, v22, v1
	v_fmac_f32_e32 v22, v1, v53
	v_cndmask_b32_e64 v1, v24, v22, s[50:51]
	ds_bpermute_b32 v22, v172, v1
	s_waitcnt lgkmcnt(0)
	v_fma_f32 v24, v55, v22, v23
	v_cndmask_b32_e64 v36, v24, v23, s[52:53]
	v_fma_f32 v23, v57, v22, v1
	v_fmac_f32_e32 v22, v1, v58
	v_cndmask_b32_e64 v29, v23, v22, s[52:53]
	ds_write_b64 v175, v[28:29] offset:59008
	s_waitcnt lgkmcnt(1)
	v_mfma_f32_16x16x32_bf16 v[22:25], v[14:17], v[208:211], 0
	s_waitcnt lgkmcnt(0)
	v_mfma_f32_16x16x32_bf16 v[102:105], v[14:17], v[212:215], 0
	ds_read_b32 v55, v174 offset:57856
	ds_read_b32 v57, v174 offset:58112
	ds_read_b32 v58, v174 offset:58368
	s_waitcnt lgkmcnt(4)
	v_mfma_f32_16x16x32_bf16 v[26:29], v[18:21], v[216:219], v[22:25]
	s_waitcnt lgkmcnt(3)
	v_mfma_f32_16x16x32_bf16 v[22:25], v[18:21], v[220:223], v[102:105]
	ds_read_b32 v246, v174 offset:57920
	ds_read_b32 v247, v174 offset:58176
	ds_read_b32 v248, v174 offset:58432
	ds_read_b128 v[208:211], v132 offset:39680
	ds_read_b128 v[212:215], v132 offset:48896
	ds_read_b128 v[216:219], v132 offset:39744
	ds_read_b128 v[220:223], v132 offset:48960
	s_waitcnt lgkmcnt(2)
	s_nop 4
	v_add_f32_e32 v1, v29, v55
	v_mul_f32_e32 v1, 0xbfb8aa3b, v1
	v_exp_f32_e32 v1, v1
	s_nop 0
	v_add_f32_e32 v1, 1.0, v1
	v_rcp_f32_e32 v1, v1
	s_waitcnt lgkmcnt(1)
	v_add_f32_e32 v25, v25, v57
	v_mul_f32_e32 v25, 0xbfb8aa3b, v25
	v_exp_f32_e32 v25, v25
	s_waitcnt lgkmcnt(0)
	v_mul_f32_e32 v1, v1, v58
	v_mul_f32_e32 v1, 0xbfb8aa3b, v1
	v_exp_f32_e32 v100, v1
	v_add_f32_e32 v25, 1.0, v25
	v_rcp_f32_e32 v25, v25
	v_add_f32_e32 v23, v23, v57
	v_sub_f32_e32 v1, 1.0, v100
	v_add_f32_e32 v29, 1.0, v100
	v_mul_f32_e32 v1, v1, v29
	v_sqrt_f32_e32 v1, v1
	v_mul_f32_e32 v101, v101, v25
	v_mul_f32_e32 v23, 0xbfb8aa3b, v23
	v_exp_f32_e32 v23, v23
	v_pk_mul_f32 v[102:103], v[100:101], v[0:1]
	v_add_f32_e32 v24, v24, v57
	v_pk_fma_f32 v[114:115], v[100:101], v[0:1], v[102:103] op_sel_hi:[1,1,0]
	v_add_f32_e32 v1, v28, v55
	v_mul_f32_e32 v1, 0xbfb8aa3b, v1
	v_exp_f32_e32 v1, v1
	v_add_f32_e32 v23, 1.0, v23
	v_rcp_f32_e32 v23, v23
	v_mul_f32_e32 v24, 0xbfb8aa3b, v24
	v_add_f32_e32 v1, 1.0, v1
	v_rcp_f32_e32 v1, v1
	v_mul_f32_e32 v23, v108, v23
	v_exp_f32_e32 v24, v24
	v_add_f32_e32 v22, v22, v57
	v_mul_f32_e32 v1, v1, v58
	v_mul_f32_e32 v1, 0xbfb8aa3b, v1
	v_exp_f32_e32 v105, v1
	v_mul_f32_e32 v22, 0xbfb8aa3b, v22
	v_add_f32_e32 v24, 1.0, v24
	v_exp_f32_e32 v22, v22
	v_sub_f32_e32 v1, 1.0, v105
	v_add_f32_e32 v25, 1.0, v105
	v_mul_f32_e32 v1, v1, v25
	v_add_f32_e32 v25, v27, v55
	v_mul_f32_e32 v25, 0xbfb8aa3b, v25
	v_exp_f32_e32 v25, v25
	v_rcp_f32_e32 v24, v24
	v_sqrt_f32_e32 v104, v1
	v_add_f32_e32 v22, 1.0, v22
	v_add_f32_e32 v25, 1.0, v25
	v_rcp_f32_e32 v25, v25
	v_mul_f32_e32 v114, v106, v24
	v_rcp_f32_e32 v22, v22
	v_pk_mul_f32 v[106:107], v[114:115], v[104:105]
	v_mul_f32_e32 v25, v25, v58
	v_mul_f32_e32 v25, 0xbfb8aa3b, v25
	v_exp_f32_e32 v51, v25
	v_add_f32_e32 v1, v106, v107
	v_mul_f32_e32 v24, v100, v105
	v_mul_f32_e32 v22, v110, v22
	v_sub_f32_e32 v25, 1.0, v51
	v_add_f32_e32 v27, 1.0, v51
	v_mul_f32_e32 v25, v25, v27
	v_sqrt_f32_e32 v25, v25
	v_mul_f32_e32 v1, v51, v1
	v_mul_f32_e32 v24, v51, v24
	v_mul_f32_e32 v53, v23, v25
	v_add_f32_e32 v23, v26, v55
	v_mul_f32_e32 v23, 0xbfb8aa3b, v23
	v_exp_f32_e32 v23, v23
	s_nop 0
	v_add_f32_e32 v23, 1.0, v23
	v_rcp_f32_e32 v23, v23
	s_nop 0
	v_mul_f32_e32 v23, v23, v58
	v_mul_f32_e32 v23, 0xbfb8aa3b, v23
	v_exp_f32_e32 v109, v23
	s_nop 0
	v_sub_f32_e32 v23, 1.0, v109
	v_add_f32_e32 v25, 1.0, v109
	v_mul_f32_e32 v23, v23, v25
	v_sqrt_f32_e32 v108, v23
	v_add_f32_e32 v23, v1, v53
	v_pk_mul_f32 v[110:111], v[22:23], v[108:109]
	s_nop 0
	v_add_f32_e32 v1, v110, v111
	v_mul_f32_e32 v22, v109, v24
	ds_bpermute_b32 v23, v171, v22
	ds_bpermute_b32 v24, v171, v1
	s_waitcnt lgkmcnt(1)
; #define LAS __attribute__((address_space(3)))
; #define MFMA16(a, b, c) __builtin_amdgcn_mfma_f32_16x16x32_bf16(a, b, c, 0, 0, 0)
; template <bool PHASE_B>
; __device__ __forceinline__ void lru_item(const Params& p, LAS unsigned char* lds, int ci, int ci_next, int jb, const int tid, v4u (&xvn)[3]) {
;     ...
;                 const bf16x8 wa = *(const LAS bf16x8*)(lds + LR_WG + ((dir * 2 + 0) * 64 + 16 * ct + fr) * 144 + (32 * ks + 8 * fq) * 2);
;                 const bf16x8 wx = *(const LAS bf16x8*)(lds + LR_WG + ((dir * 2 + 1) * 64 + 16 * ct + fr) * 144 + (32 * ks + 8 * fq) * 2);
;                 ga = MFMA16(af[ks], wa, ga); gx = MFMA16(af[ks], wx, gx); }
;             const int ch = 16 * ct + fr; const float bav = GC[(dir * 3 + 0) * 64 + ch], bxv = GC[(dir * 3 + 1) * 64 + ch], c8 = GC[(dir * 3 + 2) * 64 + ch];
;             float Al = 1.f, Hl = 0.f;
; #pragma unroll
;             for (int ee = 0; ee < 4; ++ee) { const int e = dir ? 3 - ee : ee;
;                 const float r = __builtin_amdgcn_rcpf(1.f + __expf(-(ga[e] + bav))), ig = __builtin_amdgcn_rcpf(1.f + __expf(-(gx[e] + bxv)));
;                 const float la = -c8 * r; const float a = __expf(la); const float u = __builtin_amdgcn_sqrtf((1.f - a) * (1.f + a)) * (ig * xc[ct][e]);
;                 av[dir][ct][e] = a; uv[dir][ct][e] = u; Hl = a * Hl + u; Al *= a; }
;             const int o = dir ? 3 - fq : fq; const bool odd = (o & 1) != 0, hi2 = (o & 2) != 0;
;             const float A1 = __shfl_xor(Al, 16), H1 = __shfl_xor(Hl, 16);
;             const float pxA = odd ? A1 : 1.f, pxH = odd ? H1 : 0.f;
;             const float gA = Al * A1, gH = odd ? (Al * H1 + Hl) : (A1 * Hl + H1);
;             const float A2 = __shfl_xor(gA, 32), H2 = __shfl_xor(gH, 32);
;             const float PA = hi2 ? pxA * A2 : pxA, PH = hi2 ? (pxA * H2 + pxH) : pxH;
;             const float TA = gA * A2, TH = hi2 ? (gA * H2 + gH) : (A2 * gH + H2);
;             pA[dir][ct] = PA; pH[dir][ct] = PH;
;             ((LAS f32x2*)(lds + LR_SEG))[(dir * 8 + rt) * 64 + ch] = (f32x2){TA, TH};
	v_mul_f32_e32 v27, v22, v23
	s_waitcnt lgkmcnt(0)
	v_cndmask_b32_e64 v26, v24, 0, s[54:55]
	v_fma_f32 v22, v22, v24, v1
	v_fmac_f32_e32 v24, v1, v23
	v_cndmask_b32_e64 v25, v23, 1.0, s[54:55]
	v_cndmask_b32_e64 v1, v22, v24, s[54:55]
	ds_bpermute_b32 v23, v172, v27
	ds_bpermute_b32 v24, v172, v1
	s_waitcnt lgkmcnt(1)
	v_mul_f32_e32 v22, v25, v23
	v_cndmask_b32_e64 v55, v22, v25, s[56:57]
	s_waitcnt lgkmcnt(0)
	v_fma_f32 v22, v25, v24, v26
	v_fma_f32 v25, v27, v24, v1
	v_fmac_f32_e32 v24, v1, v23
	v_cndmask_b32_e64 v57, v22, v26, s[56:57]
	v_mul_f32_e32 v22, v27, v23
	v_cndmask_b32_e64 v23, v25, v24, s[56:57]
	ds_write_b64 v175, v[22:23] offset:62720
	s_waitcnt lgkmcnt(1)
	v_mfma_f32_16x16x32_bf16 v[22:25], v[14:17], v[208:211], 0
	s_waitcnt lgkmcnt(0)
	v_mfma_f32_16x16x32_bf16 v[114:117], v[14:17], v[212:215], 0
	s_waitcnt lgkmcnt(4)
	v_mfma_f32_16x16x32_bf16 v[26:29], v[18:21], v[216:219], v[22:25]
	s_waitcnt lgkmcnt(3)
	v_mfma_f32_16x16x32_bf16 v[22:25], v[18:21], v[220:223], v[114:117]
	ds_read_b32 v224, v174 offset:57984
	ds_read_b32 v225, v174 offset:58240
	ds_read_b32 v226, v174 offset:58496
	ds_read_b128 v[208:211], v132 offset:41984
	ds_read_b128 v[212:215], v132 offset:51200
	ds_read_b128 v[216:219], v132 offset:42048
	ds_read_b128 v[220:223], v132 offset:51264
	s_waitcnt lgkmcnt(2)
	s_nop 4
	v_add_f32_e32 v1, v29, v246
	v_mul_f32_e32 v1, 0xbfb8aa3b, v1
	v_exp_f32_e32 v1, v1
	s_nop 0
	v_add_f32_e32 v1, 1.0, v1
	v_rcp_f32_e32 v1, v1
	s_waitcnt lgkmcnt(1)
	v_add_f32_e32 v25, v25, v247
	v_mul_f32_e32 v25, 0xbfb8aa3b, v25
	v_exp_f32_e32 v25, v25
	s_waitcnt lgkmcnt(0)
	v_mul_f32_e32 v1, v1, v248
	v_mul_f32_e32 v1, 0xbfb8aa3b, v1
	v_exp_f32_e32 v112, v1
	v_add_f32_e32 v25, 1.0, v25
	v_rcp_f32_e32 v25, v25
	v_add_f32_e32 v23, v23, v247
	v_sub_f32_e32 v1, 1.0, v112
	v_add_f32_e32 v29, 1.0, v112
	v_mul_f32_e32 v1, v1, v29
	v_sqrt_f32_e32 v1, v1
	v_mul_f32_e32 v113, v113, v25
	v_mul_f32_e32 v23, 0xbfb8aa3b, v23
	v_exp_f32_e32 v23, v23
	v_pk_mul_f32 v[114:115], v[112:113], v[0:1]
	v_add_f32_e32 v24, v24, v247
	v_pk_fma_f32 v[126:127], v[112:113], v[0:1], v[114:115] op_sel_hi:[1,1,0]
	v_add_f32_e32 v1, v28, v246
	v_mul_f32_e32 v1, 0xbfb8aa3b, v1
	v_exp_f32_e32 v1, v1
	v_add_f32_e32 v23, 1.0, v23
	v_rcp_f32_e32 v23, v23
	v_mul_f32_e32 v24, 0xbfb8aa3b, v24
	v_add_f32_e32 v1, 1.0, v1
	v_rcp_f32_e32 v1, v1
	v_mul_f32_e32 v23, v120, v23
	v_exp_f32_e32 v24, v24
	v_add_f32_e32 v22, v22, v247
	v_mul_f32_e32 v1, v1, v248
	v_mul_f32_e32 v1, 0xbfb8aa3b, v1
	v_exp_f32_e32 v117, v1
	v_mul_f32_e32 v22, 0xbfb8aa3b, v22
	v_add_f32_e32 v24, 1.0, v24
	v_exp_f32_e32 v22, v22
	v_sub_f32_e32 v1, 1.0, v117
	v_add_f32_e32 v25, 1.0, v117
	v_mul_f32_e32 v1, v1, v25
	v_add_f32_e32 v25, v27, v246
	v_mul_f32_e32 v25, 0xbfb8aa3b, v25
	v_exp_f32_e32 v25, v25
	v_rcp_f32_e32 v24, v24
	v_sqrt_f32_e32 v116, v1
	v_add_f32_e32 v22, 1.0, v22
	v_add_f32_e32 v25, 1.0, v25
	v_rcp_f32_e32 v25, v25
	v_mul_f32_e32 v126, v118, v24
	v_rcp_f32_e32 v22, v22
	v_pk_mul_f32 v[118:119], v[126:127], v[116:117]
	v_mul_f32_e32 v25, v25, v248
	v_mul_f32_e32 v25, 0xbfb8aa3b, v25
	v_exp_f32_e32 v58, v25
	v_add_f32_e32 v1, v118, v119
	v_mul_f32_e32 v24, v112, v117
	v_mul_f32_e32 v22, v122, v22
	v_sub_f32_e32 v25, 1.0, v58
	v_add_f32_e32 v27, 1.0, v58
	v_mul_f32_e32 v25, v25, v27
	v_sqrt_f32_e32 v25, v25
	v_mul_f32_e32 v1, v58, v1
	v_mul_f32_e32 v24, v58, v24
	v_mul_f32_e32 v60, v23, v25
	v_add_f32_e32 v23, v26, v246
	v_mul_f32_e32 v23, 0xbfb8aa3b, v23
	v_exp_f32_e32 v23, v23
	s_nop 0
	v_add_f32_e32 v23, 1.0, v23
	v_rcp_f32_e32 v23, v23
	s_nop 0
	v_mul_f32_e32 v23, v23, v248
	v_mul_f32_e32 v23, 0xbfb8aa3b, v23
	v_exp_f32_e32 v121, v23
	s_nop 0
	v_sub_f32_e32 v23, 1.0, v121
	v_add_f32_e32 v25, 1.0, v121
	v_mul_f32_e32 v23, v23, v25
	v_sqrt_f32_e32 v120, v23
	v_add_f32_e32 v23, v1, v60
	v_pk_mul_f32 v[122:123], v[22:23], v[120:121]
	s_nop 0
	v_add_f32_e32 v1, v122, v123
	v_mul_f32_e32 v22, v121, v24
	ds_bpermute_b32 v23, v171, v22
	ds_bpermute_b32 v24, v171, v1
	s_waitcnt lgkmcnt(1)
	v_mul_f32_e32 v27, v22, v23
	s_waitcnt lgkmcnt(0)
	v_cndmask_b32_e64 v26, v24, 0, s[54:55]
	v_fma_f32 v22, v22, v24, v1
	v_fmac_f32_e32 v24, v1, v23
	v_cndmask_b32_e64 v25, v23, 1.0, s[54:55]
	v_cndmask_b32_e64 v1, v22, v24, s[54:55]
	ds_bpermute_b32 v23, v172, v27
	ds_bpermute_b32 v24, v172, v1
	s_waitcnt lgkmcnt(1)
	v_mul_f32_e32 v22, v25, v23
	v_cndmask_b32_e64 v62, v22, v25, s[56:57]
	s_waitcnt lgkmcnt(0)
	v_fma_f32 v22, v25, v24, v26
	v_fma_f32 v25, v27, v24, v1
	v_fmac_f32_e32 v24, v1, v23
	v_cndmask_b32_e64 v64, v22, v26, s[56:57]
	v_mul_f32_e32 v22, v27, v23
	v_cndmask_b32_e64 v23, v25, v24, s[56:57]
	ds_write_b64 v175, v[22:23] offset:62848
	s_waitcnt lgkmcnt(1)
	v_mfma_f32_16x16x32_bf16 v[22:25], v[14:17], v[208:211], 0
	s_waitcnt lgkmcnt(0)
	v_mfma_f32_16x16x32_bf16 v[138:141], v[14:17], v[212:215], 0
	s_waitcnt lgkmcnt(4)
	v_mfma_f32_16x16x32_bf16 v[26:29], v[18:21], v[216:219], v[22:25]
	s_waitcnt lgkmcnt(3)
	v_mfma_f32_16x16x32_bf16 v[22:25], v[18:21], v[220:223], v[138:141]
	ds_read_b32 v227, v174 offset:58048
	ds_read_b32 v228, v174 offset:58304
	ds_read_b32 v229, v174 offset:58560
	ds_read_b128 v[208:211], v132 offset:44288
	ds_read_b128 v[212:215], v132 offset:53504
	ds_read_b128 v[216:219], v132 offset:44352
	ds_read_b128 v[220:223], v132 offset:53568
	s_waitcnt lgkmcnt(2)
	s_nop 4
	v_add_f32_e32 v1, v29, v224
	v_mul_f32_e32 v1, 0xbfb8aa3b, v1
	v_exp_f32_e32 v1, v1
	s_nop 0
	v_add_f32_e32 v1, 1.0, v1
	v_rcp_f32_e32 v1, v1
	s_waitcnt lgkmcnt(1)
	v_add_f32_e32 v25, v25, v225
	v_mul_f32_e32 v25, 0xbfb8aa3b, v25
	v_exp_f32_e32 v25, v25
	s_waitcnt lgkmcnt(0)
; #define LAS __attribute__((address_space(3)))
; #define MFMA16(a, b, c) __builtin_amdgcn_mfma_f32_16x16x32_bf16(a, b, c, 0, 0, 0)
; template <bool PHASE_B>
; __device__ __forceinline__ void lru_item(const Params& p, LAS unsigned char* lds, int ci, int ci_next, int jb, const int tid, v4u (&xvn)[3]) {
;     ...
;                 const bf16x8 wa = *(const LAS bf16x8*)(lds + LR_WG + ((dir * 2 + 0) * 64 + 16 * ct + fr) * 144 + (32 * ks + 8 * fq) * 2);
;                 const bf16x8 wx = *(const LAS bf16x8*)(lds + LR_WG + ((dir * 2 + 1) * 64 + 16 * ct + fr) * 144 + (32 * ks + 8 * fq) * 2);
;                 ga = MFMA16(af[ks], wa, ga); gx = MFMA16(af[ks], wx, gx); }
;             const int ch = 16 * ct + fr; const float bav = GC[(dir * 3 + 0) * 64 + ch], bxv = GC[(dir * 3 + 1) * 64 + ch], c8 = GC[(dir * 3 + 2) * 64 + ch];
;             float Al = 1.f, Hl = 0.f;
; #pragma unroll
;             for (int ee = 0; ee < 4; ++ee) { const int e = dir ? 3 - ee : ee;
;                 const float r = __builtin_amdgcn_rcpf(1.f + __expf(-(ga[e] + bav))), ig = __builtin_amdgcn_rcpf(1.f + __expf(-(gx[e] + bxv)));
;                 const float la = -c8 * r; const float a = __expf(la); const float u = __builtin_amdgcn_sqrtf((1.f - a) * (1.f + a)) * (ig * xc[ct][e]);
;                 av[dir][ct][e] = a; uv[dir][ct][e] = u; Hl = a * Hl + u; Al *= a; }
;             const int o = dir ? 3 - fq : fq; const bool odd = (o & 1) != 0, hi2 = (o & 2) != 0;
;             const float A1 = __shfl_xor(Al, 16), H1 = __shfl_xor(Hl, 16);
;             const float pxA = odd ? A1 : 1.f, pxH = odd ? H1 : 0.f;
;             const float gA = Al * A1, gH = odd ? (Al * H1 + Hl) : (A1 * Hl + H1);
;             const float A2 = __shfl_xor(gA, 32), H2 = __shfl_xor(gH, 32);
;             const float PA = hi2 ? pxA * A2 : pxA, PH = hi2 ? (pxA * H2 + pxH) : pxH;
;             const float TA = gA * A2, TH = hi2 ? (gA * H2 + gH) : (A2 * gH + H2);
;             pA[dir][ct] = PA; pH[dir][ct] = PH;
;             ((LAS f32x2*)(lds + LR_SEG))[(dir * 8 + rt) * 64 + ch] = (f32x2){TA, TH};
	v_mul_f32_e32 v1, v1, v226
	v_mul_f32_e32 v1, 0xbfb8aa3b, v1
	v_exp_f32_e32 v124, v1
	v_add_f32_e32 v25, 1.0, v25
	v_rcp_f32_e32 v25, v25
	v_add_f32_e32 v24, v24, v225
	v_sub_f32_e32 v1, 1.0, v124
	v_add_f32_e32 v29, 1.0, v124
	v_mul_f32_e32 v1, v1, v29
	v_sqrt_f32_e32 v1, v1
	v_mul_f32_e32 v125, v125, v25
	v_mul_f32_e32 v24, 0xbfb8aa3b, v24
	v_exp_f32_e32 v24, v24
	v_pk_mul_f32 v[126:127], v[124:125], v[0:1]
	v_add_f32_e32 v23, v23, v225
	v_pk_fma_f32 v[134:135], v[124:125], v[0:1], v[126:127] op_sel_hi:[1,1,0]
	v_add_f32_e32 v1, v28, v224
	v_mul_f32_e32 v1, 0xbfb8aa3b, v1
	v_exp_f32_e32 v1, v1
	v_add_f32_e32 v24, 1.0, v24
	v_rcp_f32_e32 v24, v24
	v_mul_f32_e32 v23, 0xbfb8aa3b, v23
	v_add_f32_e32 v1, 1.0, v1
	v_rcp_f32_e32 v1, v1
	v_mul_f32_e32 v134, v128, v24
	v_exp_f32_e32 v23, v23
	v_add_f32_e32 v22, v22, v225
	v_mul_f32_e32 v1, v1, v226
	v_mul_f32_e32 v1, 0xbfb8aa3b, v1
	v_exp_f32_e32 v29, v1
	v_add_f32_e32 v23, 1.0, v23
	v_rcp_f32_e32 v23, v23
	v_mul_f32_e32 v22, 0xbfb8aa3b, v22
	v_sub_f32_e32 v1, 1.0, v29
	v_add_f32_e32 v25, 1.0, v29
	v_mul_f32_e32 v1, v1, v25
	v_add_f32_e32 v25, v27, v224
	v_mul_f32_e32 v25, 0xbfb8aa3b, v25
	v_exp_f32_e32 v25, v25
	v_sqrt_f32_e32 v28, v1
	v_mul_f32_e32 v23, v130, v23
	v_exp_f32_e32 v22, v22
	v_add_f32_e32 v25, 1.0, v25
	v_rcp_f32_e32 v25, v25
	v_pk_mul_f32 v[128:129], v[134:135], v[28:29]
	v_add_f32_e32 v22, 1.0, v22
	v_rcp_f32_e32 v22, v22
	v_mul_f32_e32 v25, v25, v226
	v_mul_f32_e32 v25, 0xbfb8aa3b, v25
	v_exp_f32_e32 v28, v25
	v_add_f32_e32 v1, v128, v129
	v_mul_f32_e32 v24, v124, v29
	v_mul_f32_e32 v22, v69, v22
	v_sub_f32_e32 v25, 1.0, v28
	v_add_f32_e32 v27, 1.0, v28
	v_mul_f32_e32 v25, v25, v27
	v_sqrt_f32_e32 v25, v25
	v_mul_f32_e32 v1, v28, v1
	v_mul_f32_e32 v24, v28, v24
	v_mul_f32_e32 v67, v23, v25
	v_add_f32_e32 v23, v26, v224
	v_mul_f32_e32 v23, 0xbfb8aa3b, v23
	v_exp_f32_e32 v23, v23
	s_nop 0
	v_add_f32_e32 v23, 1.0, v23
	v_rcp_f32_e32 v23, v23
	s_nop 0
	v_mul_f32_e32 v23, v23, v226
	v_mul_f32_e32 v23, 0xbfb8aa3b, v23
	v_exp_f32_e32 v27, v23
	s_nop 0
	v_sub_f32_e32 v23, 1.0, v27
	v_add_f32_e32 v25, 1.0, v27
	v_mul_f32_e32 v23, v23, v25
	v_sqrt_f32_e32 v26, v23
	v_add_f32_e32 v23, v1, v67
	v_pk_mul_f32 v[130:131], v[22:23], v[26:27]
	s_nop 0
	v_add_f32_e32 v1, v130, v131
	v_mul_f32_e32 v22, v27, v24
	ds_bpermute_b32 v23, v171, v22
	ds_bpermute_b32 v24, v171, v1
	s_waitcnt lgkmcnt(1)
	v_mul_f32_e32 v73, v22, v23
	s_waitcnt lgkmcnt(0)
	v_cndmask_b32_e64 v69, v24, 0, s[54:55]
	v_fma_f32 v22, v22, v24, v1
	v_fmac_f32_e32 v24, v1, v23
	v_cndmask_b32_e64 v25, v23, 1.0, s[54:55]
	v_cndmask_b32_e64 v1, v22, v24, s[54:55]
	ds_bpermute_b32 v23, v172, v73
	ds_bpermute_b32 v24, v172, v1
	s_waitcnt lgkmcnt(1)
	v_mul_f32_e32 v22, v25, v23
	v_cndmask_b32_e64 v26, v22, v25, s[56:57]
	s_waitcnt lgkmcnt(0)
	v_fma_f32 v22, v25, v24, v69
	v_fma_f32 v25, v73, v24, v1
	v_fmac_f32_e32 v24, v1, v23
	v_cndmask_b32_e64 v69, v22, v69, s[56:57]
	v_mul_f32_e32 v22, v73, v23
	v_cndmask_b32_e64 v23, v25, v24, s[56:57]
	ds_write_b64 v175, v[22:23] offset:62976
	s_waitcnt lgkmcnt(1)
	v_mfma_f32_16x16x32_bf16 v[22:25], v[14:17], v[208:211], 0
	s_waitcnt lgkmcnt(0)
	v_mfma_f32_16x16x32_bf16 v[14:17], v[14:17], v[212:215], 0
	s_waitcnt lgkmcnt(1)
	v_mfma_f32_16x16x32_bf16 v[22:25], v[18:21], v[216:219], v[22:25]
	s_waitcnt lgkmcnt(0)
	v_mfma_f32_16x16x32_bf16 v[14:17], v[18:21], v[220:223], v[14:17]
	s_waitcnt lgkmcnt(2)
	s_nop 1
	s_nop 2
	v_add_f32_e32 v1, v25, v227
	v_mul_f32_e32 v1, 0xbfb8aa3b, v1
	v_exp_f32_e32 v1, v1
	s_waitcnt lgkmcnt(1)
	s_nop 0
	v_add_f32_e32 v17, v17, v228
	v_mul_f32_e32 v17, 0xbfb8aa3b, v17
	v_exp_f32_e32 v17, v17
	v_add_f32_e32 v1, 1.0, v1
	v_rcp_f32_e32 v1, v1
	v_add_f32_e32 v16, v16, v228
	v_add_f32_e32 v17, 1.0, v17
	v_rcp_f32_e32 v17, v17
	s_waitcnt lgkmcnt(0)
	v_mul_f32_e32 v1, v1, v229
	v_mul_f32_e32 v1, 0xbfb8aa3b, v1
	v_exp_f32_e32 v132, v1
	v_mul_f32_e32 v133, v133, v17
	v_mul_f32_e32 v16, 0xbfb8aa3b, v16
	v_exp_f32_e32 v16, v16
	v_sub_f32_e32 v1, 1.0, v132
	v_add_f32_e32 v18, 1.0, v132
	v_mul_f32_e32 v1, v1, v18
	v_sqrt_f32_e32 v1, v1
	v_add_f32_e32 v16, 1.0, v16
	v_add_f32_e32 v15, v15, v228
	v_rcp_f32_e32 v16, v16
	v_pk_mul_f32 v[134:135], v[132:133], v[0:1]
	v_mul_f32_e32 v15, 0xbfb8aa3b, v15
	v_pk_fma_f32 v[18:19], v[132:133], v[0:1], v[134:135] op_sel_hi:[1,1,0]
	v_add_f32_e32 v1, v24, v227
	v_mul_f32_e32 v1, 0xbfb8aa3b, v1
	v_exp_f32_e32 v1, v1
	v_exp_f32_e32 v15, v15
	v_mul_f32_e32 v18, v136, v16
	v_add_f32_e32 v14, v14, v228
	v_add_f32_e32 v1, 1.0, v1
	v_rcp_f32_e32 v1, v1
	v_add_f32_e32 v15, 1.0, v15
	v_rcp_f32_e32 v15, v15
	v_mul_f32_e32 v14, 0xbfb8aa3b, v14
	v_mul_f32_e32 v1, v1, v229
	v_mul_f32_e32 v1, 0xbfb8aa3b, v1
	v_exp_f32_e32 v25, v1
	v_mul_f32_e32 v15, v31, v15
	v_exp_f32_e32 v14, v14
	v_sub_f32_e32 v1, 1.0, v25
	v_add_f32_e32 v17, 1.0, v25
	v_mul_f32_e32 v1, v1, v17
	v_sqrt_f32_e32 v24, v1
	v_add_f32_e32 v1, v23, v227
	v_mul_f32_e32 v1, 0xbfb8aa3b, v1
	v_exp_f32_e32 v1, v1
	v_pk_mul_f32 v[136:137], v[18:19], v[24:25]
	v_mul_f32_e32 v17, v132, v25
	v_add_f32_e32 v16, v136, v137
	v_add_f32_e32 v1, 1.0, v1
	v_rcp_f32_e32 v1, v1
	v_add_f32_e32 v14, 1.0, v14
	v_rcp_f32_e32 v14, v14
	v_mul_f32_e32 v1, v1, v229
	v_mul_f32_e32 v1, 0xbfb8aa3b, v1
	v_exp_f32_e32 v1, v1
	v_mul_f32_e32 v14, v71, v14
	v_sub_f32_e32 v18, 1.0, v1
	v_add_f32_e32 v19, 1.0, v1
	v_mul_f32_e32 v18, v18, v19
	v_sqrt_f32_e32 v18, v18
	s_nop 0
	v_mul_f32_e32 v24, v15, v18
	v_mul_f32_e32 v15, v1, v16
	v_mul_f32_e32 v16, v1, v17
	v_add_f32_e32 v17, v22, v227
	v_mul_f32_e32 v17, 0xbfb8aa3b, v17
	v_exp_f32_e32 v17, v17
	v_add_f32_e32 v15, v15, v24
	v_add_f32_e32 v17, 1.0, v17
	v_rcp_f32_e32 v17, v17
	s_nop 0
	v_mul_f32_e32 v17, v17, v229
	v_mul_f32_e32 v17, 0xbfb8aa3b, v17
	v_exp_f32_e32 v23, v17
	s_nop 0
	v_sub_f32_e32 v17, 1.0, v23
	v_add_f32_e32 v18, 1.0, v23
	v_mul_f32_e32 v17, v17, v18
	v_sqrt_f32_e32 v22, v17
	s_nop 0
	v_pk_mul_f32 v[138:139], v[14:15], v[22:23]
	s_nop 0
	v_add_f32_e32 v14, v138, v139
	v_mul_f32_e32 v15, v23, v16
	ds_bpermute_b32 v16, v171, v15
	ds_bpermute_b32 v17, v171, v14
	s_waitcnt lgkmcnt(1)
; #define LAS __attribute__((address_space(3)))
; template <bool PHASE_B>
; __device__ __forceinline__ void lru_item(const Params& p, LAS unsigned char* lds, int ci, int ci_next, int jb, const int tid, v4u (&xvn)[3]) {
;     ...
;             const int o = dir ? 3 - fq : fq; const bool odd = (o & 1) != 0, hi2 = (o & 2) != 0;
;             const float A1 = __shfl_xor(Al, 16), H1 = __shfl_xor(Hl, 16);
;             const float pxA = odd ? A1 : 1.f, pxH = odd ? H1 : 0.f;
;             const float gA = Al * A1, gH = odd ? (Al * H1 + Hl) : (A1 * Hl + H1);
;             const float A2 = __shfl_xor(gA, 32), H2 = __shfl_xor(gH, 32);
;             const float PA = hi2 ? pxA * A2 : pxA, PH = hi2 ? (pxA * H2 + pxH) : pxH;
;             const float TA = gA * A2, TH = hi2 ? (gA * H2 + gH) : (A2 * gH + H2);
;             pA[dir][ct] = PA; pH[dir][ct] = PH;
;             ((LAS f32x2*)(lds + LR_SEG))[(dir * 8 + rt) * 64 + ch] = (f32x2){TA, TH};
;         }
;     }
;     if constexpr (PHASE_B) {
; #pragma unroll
;         for (int dir = 0; dir < 2; ++dir)
; #pragma unroll
;             for (int ct = 0; ct < 4; ++ct) cin[dir][ct] = ((const float*)(p.ws + WS_CIN))[(size_t)(ci * 2 + dir) * 768 + jb * 64 + 16 * ct + fr];
;         const bf16* gp = (const bf16*)(p.ws + WS_GR) + (size_t)(t0 + (tid >> 2)) * 768 + jb * 64 + (tid & 3) * 16;
;         gv[0] = *(const v4u*)gp; gv[1] = *(const v4u*)(gp + 8);
;     }
;     __syncthreads();
;     if constexpr (!PHASE_B) {
;         if (tid < 128) { const int dir = tid >> 6, ch = tid & 63; float A = 1.f, H = 0.f;
; #pragma unroll
;             for (int q = 0; q < 8; ++q) { const f32x2 sh = ((const LAS f32x2*)(lds + LR_SEG))[(dir * 8 + (dir ? 7 - q : q)) * 64 + ch]; H = sh.x * H + sh.y; A *= sh.x; }
;             ((f32x2*)(p.ws + WS_CAR))[(size_t)(ci * 2 + dir) * 768 + jb * 64 + ch] = (f32x2){A, H}; }
;     } else {
; #pragma unroll
;         for (int dir = 0; dir < 2; ++dir) { const int ot = dir ? 7 - rt : rt;
; #pragma unroll
;             for (int ct = 0; ct < 4; ++ct) { const int ch = 16 * ct + fr; float h = cin[dir][ct];
; #pragma unroll
;                 for (int q = 0; q < 7; ++q) { const f32x2 sh = ((const LAS f32x2*)(lds + LR_SEG))[(dir * 8 + (dir ? 7 - q : q)) * 64 + ch]; const float nh = sh.x * h + sh.y; h = (q < ot) ? nh : h; }
;                 h = pA[dir][ct] * h + pH[dir][ct];
; #pragma unroll
	v_mul_f32_e32 v20, v15, v16
	s_waitcnt lgkmcnt(0)
	v_cndmask_b32_e64 v19, v17, 0, s[54:55]
	v_fma_f32 v15, v15, v17, v14
	v_fmac_f32_e32 v17, v14, v16
	v_cndmask_b32_e64 v18, v16, 1.0, s[54:55]
	v_cndmask_b32_e64 v15, v15, v17, s[54:55]
	ds_bpermute_b32 v16, v172, v20
	ds_bpermute_b32 v17, v172, v15
	s_waitcnt lgkmcnt(1)
	v_mul_f32_e32 v14, v18, v16
	v_cndmask_b32_e64 v22, v14, v18, s[56:57]
	s_waitcnt lgkmcnt(0)
	v_fma_f32 v14, v18, v17, v19
	v_fma_f32 v18, v20, v17, v15
	v_fmac_f32_e32 v17, v15, v16
	v_cndmask_b32_e64 v31, v14, v19, s[56:57]
	v_mul_f32_e32 v14, v20, v16
	v_cndmask_b32_e64 v15, v18, v17, s[56:57]
	ds_write_b64 v175, v[14:15] offset:63104
	v_mad_i64_i32 v[14:15], s[0:1], s13, v232, v[32:33]
	global_load_dword v78, v[14:15], off
	global_load_dword v81, v[14:15], off offset:64
	global_load_dword v83, v[14:15], off offset:128
	global_load_dword v85, v[14:15], off offset:192
	s_add_i32 s0, s13, 1
	v_mad_i64_i32 v[14:15], s[0:1], s0, v232, v[32:33]
	s_movk_i32 s0, 0x600
	s_nop 0
	v_mad_i64_i32 v[140:141], s[0:1], v196, s0, v[34:35]
	global_load_dword v76, v[14:15], off
	global_load_dword v74, v[14:15], off offset:64
	global_load_dword v73, v[14:15], off offset:128
	global_load_dword v71, v[14:15], off offset:192
	s_nop 0
	global_load_dwordx4 v[14:17], v[140:141], off offset:16
	global_load_dwordx4 v[18:21], v[140:141], off
	s_waitcnt lgkmcnt(0)
	s_barrier
	ds_read_b64 v[208:209], v176 offset:58624
	ds_read_b64 v[210:211], v176 offset:59136
	ds_read_b64 v[212:213], v176 offset:59648
	ds_read_b64 v[214:215], v176 offset:60160
	ds_read_b64 v[216:217], v176 offset:60672
	ds_read_b64 v[218:219], v176 offset:61184
	ds_read_b64 v[220:221], v176 offset:61696
	v_add_u32_e32 v196, s12, v196
	s_add_i32 s13, s13, s86
	s_waitcnt vmcnt(9) lgkmcnt(0)
	v_fmac_f32_e32 v209, v78, v208
	v_cndmask_b32_e64 v78, v78, v209, s[58:59]
	v_fmac_f32_e32 v211, v210, v78
	v_cndmask_b32_e64 v78, v78, v211, s[60:61]
	v_fmac_f32_e32 v213, v212, v78
	v_cndmask_b32_e64 v78, v78, v213, s[62:63]
	v_fmac_f32_e32 v215, v214, v78
	v_cndmask_b32_e64 v78, v78, v215, s[64:65]
	v_fmac_f32_e32 v217, v216, v78
	v_cndmask_b32_e64 v78, v78, v217, s[66:67]
	v_fmac_f32_e32 v219, v218, v78
	v_cndmask_b32_e64 v78, v78, v219, s[68:69]
	v_fmac_f32_e32 v221, v220, v78
	v_cndmask_b32_e64 v78, v78, v221, s[70:71]
	v_fmac_f32_e32 v39, v206, v78
	v_fmac_f32_e32 v49, v38, v39
	v_fmac_f32_e32 v50, v41, v49
	v_fmac_f32_e32 v52, v43, v50
	v_fmac_f32_e32 v54, v47, v52
	ds_write2_b32 v202, v49, v50 offset1:68
	ds_write2_b32 v202, v52, v54 offset0:136 offset1:204
	ds_read_b64 v[222:223], v176 offset:58752
	ds_read_b64 v[224:225], v176 offset:59264
	ds_read_b64 v[226:227], v176 offset:59776
	ds_read_b64 v[228:229], v176 offset:60288
	ds_read_b64 v[234:235], v176 offset:60800
	ds_read_b64 v[236:237], v176 offset:61312
	ds_read_b64 v[238:239], v176 offset:61824
	s_waitcnt vmcnt(0)
	v_lshlrev_b32_e32 v52, 16, v18
	v_and_b32_e32 v18, 0xffff0000, v18
	s_waitcnt lgkmcnt(0)
	v_fmac_f32_e32 v223, v81, v222
	v_cndmask_b32_e64 v41, v81, v223, s[58:59]
	v_fmac_f32_e32 v225, v224, v41
	v_cndmask_b32_e64 v41, v41, v225, s[60:61]
	v_fmac_f32_e32 v227, v226, v41
	v_cndmask_b32_e64 v41, v41, v227, s[62:63]
	v_fmac_f32_e32 v229, v228, v41
	v_cndmask_b32_e64 v41, v41, v229, s[64:65]
	v_fmac_f32_e32 v235, v234, v41
	v_cndmask_b32_e64 v41, v41, v235, s[66:67]
	v_fmac_f32_e32 v237, v236, v41
	v_cndmask_b32_e64 v41, v41, v237, s[68:69]
	v_fmac_f32_e32 v239, v238, v41
	v_cndmask_b32_e64 v38, v41, v239, s[70:71]
	v_fmac_f32_e32 v42, v40, v38
	v_fmac_f32_e32 v65, v56, v42
	v_fmac_f32_e32 v66, v59, v65
	v_fmac_f32_e32 v68, v61, v66
	v_fmac_f32_e32 v70, v63, v68
	ds_write_b32 v177, v65
	ds_write_b32 v178, v66
	ds_write_b32 v179, v68
	ds_write_b32 v180, v70
	ds_read_b64 v[208:209], v176 offset:58880
	ds_read_b64 v[210:211], v176 offset:59392
	ds_read_b64 v[212:213], v176 offset:59904
	ds_read_b64 v[214:215], v176 offset:60416
	ds_read_b64 v[216:217], v176 offset:60928
	ds_read_b64 v[218:219], v176 offset:61440
	ds_read_b64 v[220:221], v176 offset:61952
	s_waitcnt lgkmcnt(0)
	v_fmac_f32_e32 v209, v83, v208
	v_cndmask_b32_e64 v40, v83, v209, s[58:59]
	v_fmac_f32_e32 v211, v210, v40
	v_cndmask_b32_e64 v40, v40, v211, s[60:61]
	v_fmac_f32_e32 v213, v212, v40
	v_cndmask_b32_e64 v40, v40, v213, s[62:63]
	v_fmac_f32_e32 v215, v214, v40
	v_cndmask_b32_e64 v40, v40, v215, s[64:65]
	v_fmac_f32_e32 v217, v216, v40
	v_cndmask_b32_e64 v40, v40, v217, s[66:67]
	v_fmac_f32_e32 v219, v218, v40
	v_cndmask_b32_e64 v40, v40, v219, s[68:69]
	v_fmac_f32_e32 v221, v220, v40
	v_cndmask_b32_e64 v38, v40, v221, s[70:71]
	v_fmac_f32_e32 v44, v46, v38
	v_fmac_f32_e32 v45, v72, v44
	v_fmac_f32_e32 v80, v75, v45
	v_fmac_f32_e32 v82, v77, v80
	v_fmac_f32_e32 v84, v79, v82
	ds_write_b32 v181, v45
	ds_write_b32 v182, v80
	ds_write_b32 v183, v82
	ds_write_b32 v184, v84
	ds_read_b64 v[222:223], v176 offset:59008
	ds_read_b64 v[224:225], v176 offset:59520
	ds_read_b64 v[226:227], v176 offset:60032
	ds_read_b64 v[228:229], v176 offset:60544
	ds_read_b64 v[234:235], v176 offset:61056
	ds_read_b64 v[236:237], v176 offset:61568
	ds_read_b64 v[238:239], v176 offset:62080
	s_waitcnt lgkmcnt(0)
	v_fmac_f32_e32 v223, v85, v222
	v_cndmask_b32_e64 v40, v85, v223, s[58:59]
	v_fmac_f32_e32 v225, v224, v40
	v_cndmask_b32_e64 v40, v40, v225, s[60:61]
	v_fmac_f32_e32 v227, v226, v40
	v_cndmask_b32_e64 v40, v40, v227, s[62:63]
	v_fmac_f32_e32 v229, v228, v40
	v_cndmask_b32_e64 v40, v40, v229, s[64:65]
	v_fmac_f32_e32 v235, v234, v40
	v_cndmask_b32_e64 v40, v40, v235, s[66:67]
	v_fmac_f32_e32 v237, v236, v40
	v_cndmask_b32_e64 v40, v40, v237, s[68:69]
	v_fmac_f32_e32 v239, v238, v40
	v_cndmask_b32_e64 v38, v40, v239, s[70:71]
	v_fmac_f32_e32 v36, v48, v38
	v_fmac_f32_e32 v37, v86, v36
	v_fmac_f32_e32 v94, v89, v37
	v_fmac_f32_e32 v96, v91, v94
	v_fmac_f32_e32 v98, v93, v96
	ds_write_b32 v185, v37
	ds_write_b32 v186, v94
	ds_write_b32 v187, v96
	ds_write_b32 v188, v98
	ds_read2st64_b64 v[36:39], v190 offset0:6 offset1:7
	s_waitcnt lgkmcnt(0)
; #define LAS __attribute__((address_space(3)))
; template <bool PHASE_B>
; __device__ __forceinline__ void lru_item(const Params& p, LAS unsigned char* lds, int ci, int ci_next, int jb, const int tid, v4u (&xvn)[3]) {
;     ...
; #pragma unroll
;         for (int dir = 0; dir < 2; ++dir) { const int ot = dir ? 7 - rt : rt;
; #pragma unroll
;             for (int ct = 0; ct < 4; ++ct) { const int ch = 16 * ct + fr; float h = cin[dir][ct];
; #pragma unroll
;                 for (int q = 0; q < 7; ++q) { const f32x2 sh = ((const LAS f32x2*)(lds + LR_SEG))[(dir * 8 + (dir ? 7 - q : q)) * 64 + ch]; const float nh = sh.x * h + sh.y; h = (q < ot) ? nh : h; }
;                 h = pA[dir][ct] * h + pH[dir][ct];
; #pragma unroll
;                 for (int ee = 0; ee < 4; ++ee) { const int e = dir ? 3 - ee : ee; h = av[dir][ct][e] * h + uv[dir][ct][e];
;                     ((LAS float*)(lds + LR_HB))[(dir * LCH + 16 * rt + 4 * fq + e) * 68 + ch] = h; } } }
;         __syncthreads();
	v_fma_f32 v38, v76, v38, v39
	v_cndmask_b32_e64 v38, v76, v38, s[72:73]
	v_fmac_f32_e32 v37, v36, v38
	v_cndmask_b32_e64 v38, v38, v37, s[74:75]
	ds_read_b64 v[208:209], v176 offset:65280
	ds_read_b64 v[210:211], v176 offset:64768
	ds_read_b64 v[212:213], v176 offset:64256
	ds_read_b64 v[214:215], v176 offset:63744
	ds_read_b64 v[216:217], v176 offset:63232
	s_waitcnt lgkmcnt(0)
	v_fmac_f32_e32 v209, v208, v38
	v_cndmask_b32_e64 v38, v38, v209, s[76:77]
	v_fmac_f32_e32 v211, v210, v38
	v_cndmask_b32_e64 v38, v38, v211, s[78:79]
	v_fmac_f32_e32 v213, v212, v38
	v_cndmask_b32_e64 v38, v38, v213, s[80:81]
	v_fmac_f32_e32 v215, v214, v38
	v_cndmask_b32_e64 v38, v38, v215, s[82:83]
	v_fmac_f32_e32 v217, v216, v38
	v_cndmask_b32_e64 v36, v38, v217, s[84:85]
	v_fmac_f32_e32 v57, v55, v36
	v_fmac_f32_e32 v103, v100, v57
	v_fmac_f32_e32 v106, v105, v103
	v_fmac_f32_e32 v53, v51, v106
	v_add_u32_e32 v36, 0x8800, v202
	v_fmac_f32_e32 v110, v109, v53
	ds_write2_b32 v36, v106, v103 offset0:136 offset1:204
	ds_write2_b32 v36, v110, v53 offset1:68
	ds_read2st64_b64 v[36:39], v191 offset0:6 offset1:7
	v_lshlrev_b32_e32 v53, 16, v19
	v_and_b32_e32 v19, 0xffff0000, v19
	s_waitcnt lgkmcnt(0)
	v_fma_f32 v38, v74, v38, v39
	v_cndmask_b32_e64 v38, v74, v38, s[72:73]
	v_fmac_f32_e32 v37, v36, v38
	v_cndmask_b32_e64 v38, v38, v37, s[74:75]
	ds_read_b64 v[222:223], v176 offset:65408
	ds_read_b64 v[224:225], v176 offset:64896
	ds_read_b64 v[226:227], v176 offset:64384
	ds_read_b64 v[228:229], v176 offset:63872
	ds_read_b64 v[234:235], v176 offset:63360
	s_waitcnt lgkmcnt(0)
	v_fmac_f32_e32 v223, v222, v38
	v_cndmask_b32_e64 v38, v38, v223, s[76:77]
	v_fmac_f32_e32 v225, v224, v38
	v_cndmask_b32_e64 v38, v38, v225, s[78:79]
	v_fmac_f32_e32 v227, v226, v38
	v_cndmask_b32_e64 v38, v38, v227, s[80:81]
	v_fmac_f32_e32 v229, v228, v38
	v_cndmask_b32_e64 v38, v38, v229, s[82:83]
	v_fmac_f32_e32 v235, v234, v38
	v_cndmask_b32_e64 v36, v38, v235, s[84:85]
	v_fmac_f32_e32 v64, v62, v36
	v_fmac_f32_e32 v115, v112, v64
	v_fmac_f32_e32 v118, v117, v115
	v_fmac_f32_e32 v60, v58, v118
	v_add_u32_e32 v36, 0x8800, v203
	v_fmac_f32_e32 v122, v121, v60
	ds_write2_b32 v36, v118, v115 offset0:136 offset1:204
	ds_write2_b32 v36, v122, v60 offset1:68
	ds_read_b64 v[36:37], v192 offset:3584
	s_waitcnt lgkmcnt(0)
	v_fmac_f32_e32 v37, v73, v36
	v_cndmask_b32_e64 v40, v73, v37, s[72:73]
	ds_read2st64_b64 v[36:39], v192 offset0:5 offset1:6
	s_waitcnt lgkmcnt(0)
	v_fma_f32 v38, v38, v40, v39
	v_cndmask_b32_e64 v38, v40, v38, s[74:75]
	v_fmac_f32_e32 v37, v36, v38
	v_cndmask_b32_e64 v38, v38, v37, s[76:77]
	ds_read_b64 v[208:209], v176 offset:65024
	ds_read_b64 v[210:211], v176 offset:64512
	ds_read_b64 v[212:213], v176 offset:64000
	ds_read_b64 v[214:215], v176 offset:63488
	s_waitcnt lgkmcnt(0)
	v_fmac_f32_e32 v209, v208, v38
	v_cndmask_b32_e64 v38, v38, v209, s[78:79]
	v_fmac_f32_e32 v211, v210, v38
	v_cndmask_b32_e64 v38, v38, v211, s[80:81]
	v_fmac_f32_e32 v213, v212, v38
	v_cndmask_b32_e64 v38, v38, v213, s[82:83]
	v_fmac_f32_e32 v215, v214, v38
	v_cndmask_b32_e64 v36, v38, v215, s[84:85]
	v_fmac_f32_e32 v69, v26, v36
	v_fmac_f32_e32 v127, v124, v69
	v_fmac_f32_e32 v128, v29, v127
	v_fmac_f32_e32 v67, v28, v128
	v_add_u32_e32 v26, 0x8800, v204
	v_fmac_f32_e32 v130, v27, v67
	ds_write2_b32 v26, v128, v127 offset0:136 offset1:204
	ds_write2_b32 v26, v130, v67 offset1:68
	ds_read_b64 v[26:27], v194 offset:3584
	s_waitcnt lgkmcnt(0)
	v_fmac_f32_e32 v27, v71, v26
	v_cndmask_b32_e64 v36, v71, v27, s[72:73]
	ds_read2st64_b64 v[26:29], v194 offset0:5 offset1:6
	s_waitcnt lgkmcnt(0)
	v_fma_f32 v28, v28, v36, v29
	v_cndmask_b32_e64 v28, v36, v28, s[74:75]
	v_fmac_f32_e32 v27, v26, v28
	v_cndmask_b32_e64 v28, v28, v27, s[76:77]
	ds_read_b64 v[222:223], v176 offset:65152
	ds_read_b64 v[224:225], v176 offset:64640
	ds_read_b64 v[226:227], v176 offset:64128
	ds_read_b64 v[228:229], v176 offset:63616
	s_waitcnt lgkmcnt(0)
	v_fmac_f32_e32 v223, v222, v28
	v_cndmask_b32_e64 v28, v28, v223, s[78:79]
	v_fmac_f32_e32 v225, v224, v28
	v_cndmask_b32_e64 v28, v28, v225, s[80:81]
	v_fmac_f32_e32 v227, v226, v28
	v_cndmask_b32_e64 v28, v28, v227, s[82:83]
	v_fmac_f32_e32 v229, v228, v28
	v_cndmask_b32_e64 v26, v28, v229, s[84:85]
	v_fmac_f32_e32 v31, v22, v26
	v_fmac_f32_e32 v135, v132, v31
	v_fmac_f32_e32 v136, v25, v135
	v_fmac_f32_e32 v24, v1, v136
	v_add_u32_e32 v22, 0x8800, v205
	v_fmac_f32_e32 v138, v23, v24
	ds_write2_b32 v22, v136, v135 offset0:136 offset1:204
	ds_write2_b32 v22, v138, v24 offset1:68
	s_waitcnt lgkmcnt(0)
	s_barrier
; #define LAS __attribute__((address_space(3)))
; __device__ __forceinline__ unsigned pk2(float lo, float hi) { return f2bf(lo) | (f2bf(hi) << 16); }
; template <bool PHASE_B>
; __device__ __forceinline__ void lru_item(const Params& p, LAS unsigned char* lds, int ci, int ci_next, int jb, const int tid, v4u (&xvn)[3]) {
;     ...
;         { const int t = tid >> 2, c0 = (tid & 3) * 16; bf16* gp = (bf16*)(p.ws + WS_GR) + (size_t)(t0 + t) * 768 + jb * 64 + c0;
;           const LAS float* H0 = (const LAS float*)(lds + LR_HB) + t * 68 + c0; const LAS float* H1 = H0 + LCH * 68;
; #pragma unroll
;           for (int hf = 0; hf < 2; ++hf) { const f32x4 a0 = *(const LAS f32x4*)(H0 + 8 * hf), a1 = *(const LAS f32x4*)(H0 + 8 * hf + 4), b0 = *(const LAS f32x4*)(H1 + 8 * hf), b1 = *(const LAS f32x4*)(H1 + 8 * hf + 4);
;               const v4u g = gv[hf]; v4u o;
;               o.x = pk2(bflo(g.x) * (a0[0] + b0[0]), bfhi(g.x) * (a0[1] + b0[1])); o.y = pk2(bflo(g.y) * (a0[2] + b0[2]), bfhi(g.y) * (a0[3] + b0[3]));
;               o.z = pk2(bflo(g.z) * (a1[0] + b1[0]), bfhi(g.z) * (a1[1] + b1[1])); o.w = pk2(bflo(g.w) * (a1[2] + b1[2]), bfhi(g.w) * (a1[3] + b1[3]));
;               *(v4u*)(gp + 8 * hf) = o; } }
	ds_read_b128 v[22:25], v195
	ds_read_b128 v[26:29], v195 offset:16
	ds_read_b128 v[36:39], v195 offset:32
	ds_read_b128 v[40:43], v195 offset:48
	ds_read_b128 v[44:47], v195 offset:34816
	ds_read_b128 v[48:51], v195 offset:34832
	s_waitcnt lgkmcnt(1)
	v_pk_add_f32 v[24:25], v[24:25], v[46:47]
	v_pk_add_f32 v[22:23], v[22:23], v[44:45]
	v_mov_b32_e32 v45, v24
	v_mov_b32_e32 v24, v23
	v_pk_mul_f32 v[18:19], v[24:25], v[18:19]
	s_waitcnt lgkmcnt(0)
	v_pk_add_f32 v[24:25], v[28:29], v[50:51]
	v_pk_add_f32 v[26:27], v[26:27], v[48:49]
	v_mov_b32_e32 v44, v22
	v_lshlrev_b32_e32 v23, 16, v21
	v_lshlrev_b32_e32 v22, 16, v20
	v_mov_b32_e32 v29, v24
	v_and_b32_e32 v21, 0xffff0000, v21
	v_and_b32_e32 v20, 0xffff0000, v20
	v_mov_b32_e32 v24, v27
	v_mov_b32_e32 v28, v26
	v_pk_mul_f32 v[20:21], v[24:25], v[20:21]
	v_pk_mul_f32 v[44:45], v[44:45], v[52:53]
	v_pk_mul_f32 v[22:23], v[28:29], v[22:23]
	v_bfe_u32 v1, v21, 16, 1
	v_add3_u32 v1, v21, v1, s33
	v_bfe_u32 v26, v23, 16, 1
	v_add3_u32 v23, v23, v26, s33
	v_lshrrev_b32_e32 v21, 16, v23
	v_and_or_b32 v21, v1, s11, v21
	v_cvt_pk_bf16_f32 v20, v22, v20
	v_cvt_pk_bf16_f32 v19, v45, v19
	v_cvt_pk_bf16_f32 v18, v44, v18
	global_store_dwordx4 v[140:141], v[18:21], off
	ds_read_b128 v[18:21], v195 offset:34848
	ds_read_b128 v[22:25], v195 offset:34864
	v_lshlrev_b32_e32 v27, 16, v15
	v_lshlrev_b32_e32 v26, 16, v14
	v_and_b32_e32 v15, 0xffff0000, v15
	s_waitcnt lgkmcnt(1)
	v_pk_add_f32 v[20:21], v[38:39], v[20:21]
	v_pk_add_f32 v[18:19], v[36:37], v[18:19]
	v_mov_b32_e32 v29, v20
	v_and_b32_e32 v14, 0xffff0000, v14
	v_mov_b32_e32 v20, v19
	v_pk_mul_f32 v[14:15], v[20:21], v[14:15]
	s_waitcnt lgkmcnt(0)
	v_pk_add_f32 v[20:21], v[42:43], v[24:25]
	v_pk_add_f32 v[22:23], v[40:41], v[22:23]
	v_mov_b32_e32 v28, v18
	v_lshlrev_b32_e32 v19, 16, v17
	v_lshlrev_b32_e32 v18, 16, v16
	v_mov_b32_e32 v25, v20
	v_and_b32_e32 v17, 0xffff0000, v17
	v_and_b32_e32 v16, 0xffff0000, v16
	v_mov_b32_e32 v20, v23
	v_mov_b32_e32 v24, v22
	v_pk_mul_f32 v[16:17], v[20:21], v[16:17]
	v_pk_mul_f32 v[26:27], v[28:29], v[26:27]
	v_pk_mul_f32 v[18:19], v[24:25], v[18:19]
	v_bfe_u32 v1, v17, 16, 1
	v_bfe_u32 v20, v16, 16, 1
	v_add3_u32 v16, v16, v20, s33
	v_add3_u32 v1, v17, v1, s33
	v_bfe_u32 v21, v18, 16, 1
	v_bfe_u32 v22, v19, 16, 1
	v_add3_u32 v19, v19, v22, s33
	v_add3_u32 v18, v18, v21, s33
	v_lshrrev_b32_e32 v21, 16, v17
	v_lshrrev_b32_e32 v20, 16, v20
	v_lshrrev_b32_e32 v18, 16, v18
	v_lshrrev_b32_e32 v17, 16, v19
	v_and_or_b32 v17, v1, s11, v17
	v_and_or_b32 v16, v16, s11, v18
	v_cvt_pk_bf16_f32 v15, v27, v15
	v_cvt_pk_bf16_f32 v14, v26, v14
	global_store_dwordx4 v[140:141], v[14:17], off offset:16
	s_cbranch_vccnz .LBB0_353
